# expert layer-1 LN epilogue and attnA item epilogue: loads issued together with counted waits (bit-identical), on top of the de-serialised residual epilogues
# speedup vs baseline: 1.0159x; 1.0032x over previous
.LBB0_178:
	global_load_dwordx4 v[68:71], v[114:115], off offset:240
	global_load_dwordx4 v[72:75], v[114:115], off
	global_load_dwordx4 v[76:79], v[114:115], off offset:16
	global_load_dwordx4 v[80:83], v[114:115], off offset:32
	global_load_dwordx4 v[84:87], v[114:115], off offset:48
	global_load_dwordx4 v[88:91], v[114:115], off offset:64
	global_load_dwordx4 v[92:95], v[114:115], off offset:80
	global_load_dwordx4 v[96:99], v[114:115], off offset:96
	global_load_dwordx4 v[100:103], v[114:115], off offset:112
	global_load_dwordx4 v[104:107], v[114:115], off offset:128
	global_load_dwordx4 v[108:111], v[114:115], off offset:144
	global_load_dwordx4 v[122:125], v[114:115], off offset:160
	global_load_dwordx4 v[126:129], v[114:115], off offset:176
	global_load_dwordx4 v[130:133], v[114:115], off offset:192
	global_load_dwordx4 v[134:137], v[114:115], off offset:208
	global_load_dwordx4 v[138:141], v[114:115], off offset:224
	ds_bpermute_b32 v64, v158, v144
	s_lshl_b32 s8, s25, 1
	s_waitcnt lgkmcnt(0)
	v_add_f32_e32 v112, v144, v64
	v_div_scale_f32 v119, s[14:15], v112, v112, v165
	v_rcp_f32_e32 v142, v119
	v_div_scale_f32 v143, vcc, v165, v112, v165
	global_load_dwordx4 v[64:67], v[116:117], off
	v_fma_f32 v144, -v119, v142, 1.0
	v_fmac_f32_e32 v142, v144, v142
	v_mul_f32_e32 v144, v143, v142
	v_fma_f32 v145, -v119, v144, v143
	v_fmac_f32_e32 v144, v145, v142
	v_fma_f32 v119, -v119, v144, v143
	v_div_fmas_f32 v119, v119, v142, v144
	v_div_fixup_f32 v112, v119, v112, v165
	s_waitcnt vmcnt(16)
	v_pk_fma_f32 v[68:69], v[12:13], v[112:113], v[68:69] op_sel_hi:[1,0,1] neg_lo:[1,0,0] neg_hi:[1,0,0]
	s_waitcnt vmcnt(15)
	v_pk_fma_f32 v[72:73], v[48:49], v[112:113], v[72:73] op_sel_hi:[1,0,1] neg_lo:[1,0,0] neg_hi:[1,0,0]
	v_pk_fma_f32 v[12:13], v[14:15], v[112:113], v[70:71] op_sel_hi:[1,0,1] neg_lo:[1,0,0] neg_hi:[1,0,0]
	v_pk_fma_f32 v[70:71], v[50:51], v[112:113], v[74:75] op_sel_hi:[1,0,1] neg_lo:[1,0,0] neg_hi:[1,0,0]
	s_waitcnt vmcnt(14)
	v_pk_fma_f32 v[74:75], v[54:55], v[112:113], v[78:79] op_sel_hi:[1,0,1] neg_lo:[1,0,0] neg_hi:[1,0,0]
	s_waitcnt vmcnt(12)
	v_pk_fma_f32 v[54:55], v[62:63], v[112:113], v[86:87] op_sel_hi:[1,0,1] neg_lo:[1,0,0] neg_hi:[1,0,0]
	v_pk_mul_f32 v[62:63], v[72:73], v[72:73]
	s_waitcnt vmcnt(11)
	v_pk_fma_f32 v[50:51], v[34:35], v[112:113], v[90:91] op_sel_hi:[1,0,1] neg_lo:[1,0,0] neg_hi:[1,0,0]
	s_waitcnt vmcnt(8)
	v_pk_fma_f32 v[34:35], v[46:47], v[112:113], v[102:103] op_sel_hi:[1,0,1] neg_lo:[1,0,0] neg_hi:[1,0,0]
	v_pk_mul_f32 v[46:47], v[70:71], v[70:71]
	v_add_f32_e32 v62, v62, v63
	v_pk_fma_f32 v[76:77], v[52:53], v[112:113], v[76:77] op_sel_hi:[1,0,1] neg_lo:[1,0,0] neg_hi:[1,0,0]
	v_add_f32_e32 v46, v46, v62
	v_pk_fma_f32 v[58:59], v[58:59], v[112:113], v[82:83] op_sel_hi:[1,0,1] neg_lo:[1,0,0] neg_hi:[1,0,0]
	v_pk_mul_f32 v[82:83], v[76:77], v[76:77]
	v_add_f32_e32 v46, v47, v46
	v_add_f32_e32 v46, v82, v46
	v_pk_fma_f32 v[78:79], v[56:57], v[112:113], v[80:81] op_sel_hi:[1,0,1] neg_lo:[1,0,0] neg_hi:[1,0,0]
	v_pk_mul_f32 v[80:81], v[74:75], v[74:75]
	v_add_f32_e32 v46, v83, v46
	v_add_f32_e32 v46, v80, v46
	v_pk_mul_f32 v[86:87], v[78:79], v[78:79]
	v_add_f32_e32 v46, v81, v46
	v_add_f32_e32 v46, v86, v46
	v_pk_fma_f32 v[60:61], v[60:61], v[112:113], v[84:85] op_sel_hi:[1,0,1] neg_lo:[1,0,0] neg_hi:[1,0,0]
	v_pk_mul_f32 v[84:85], v[58:59], v[58:59]
	v_add_f32_e32 v46, v87, v46
	v_add_f32_e32 v46, v84, v46
	v_pk_mul_f32 v[90:91], v[60:61], v[60:61]
	v_add_f32_e32 v46, v85, v46
	v_add_f32_e32 v46, v90, v46
	v_pk_fma_f32 v[56:57], v[32:33], v[112:113], v[88:89] op_sel_hi:[1,0,1] neg_lo:[1,0,0] neg_hi:[1,0,0]
	v_pk_mul_f32 v[88:89], v[54:55], v[54:55]
	v_add_f32_e32 v46, v91, v46
	v_add_f32_e32 v46, v88, v46
	v_pk_fma_f32 v[48:49], v[38:39], v[112:113], v[94:95] op_sel_hi:[1,0,1] neg_lo:[1,0,0] neg_hi:[1,0,0]
	v_pk_mul_f32 v[94:95], v[56:57], v[56:57]
	v_add_f32_e32 v46, v89, v46
	v_add_f32_e32 v46, v94, v46
	v_pk_fma_f32 v[52:53], v[36:37], v[112:113], v[92:93] op_sel_hi:[1,0,1] neg_lo:[1,0,0] neg_hi:[1,0,0]
	v_pk_mul_f32 v[92:93], v[50:51], v[50:51]
	v_add_f32_e32 v46, v95, v46
	v_add_f32_e32 v46, v92, v46
	v_pk_fma_f32 v[38:39], v[42:43], v[112:113], v[98:99] op_sel_hi:[1,0,1] neg_lo:[1,0,0] neg_hi:[1,0,0]
	v_pk_mul_f32 v[98:99], v[52:53], v[52:53]
	v_add_f32_e32 v46, v93, v46
	v_add_f32_e32 v46, v98, v46
	v_pk_fma_f32 v[42:43], v[40:41], v[112:113], v[96:97] op_sel_hi:[1,0,1] neg_lo:[1,0,0] neg_hi:[1,0,0]
	v_pk_mul_f32 v[96:97], v[48:49], v[48:49]
	v_add_f32_e32 v46, v99, v46
	v_add_f32_e32 v46, v96, v46
	v_pk_mul_f32 v[102:103], v[42:43], v[42:43]
	v_add_f32_e32 v46, v97, v46
	v_add_f32_e32 v46, v102, v46
	v_pk_fma_f32 v[40:41], v[44:45], v[112:113], v[100:101] op_sel_hi:[1,0,1] neg_lo:[1,0,0] neg_hi:[1,0,0]
	v_pk_mul_f32 v[100:101], v[38:39], v[38:39]
	v_add_f32_e32 v46, v103, v46
	v_add_f32_e32 v46, v100, v46
	s_waitcnt vmcnt(7)
	v_pk_fma_f32 v[32:33], v[18:19], v[112:113], v[106:107] op_sel_hi:[1,0,1] neg_lo:[1,0,0] neg_hi:[1,0,0]
	v_pk_mul_f32 v[106:107], v[40:41], v[40:41]
	v_add_f32_e32 v46, v101, v46
	v_add_f32_e32 v46, v106, v46
	v_pk_fma_f32 v[36:37], v[16:17], v[112:113], v[104:105] op_sel_hi:[1,0,1] neg_lo:[1,0,0] neg_hi:[1,0,0]
	v_pk_mul_f32 v[104:105], v[34:35], v[34:35]
	v_add_f32_e32 v46, v107, v46
	v_add_f32_e32 v46, v104, v46
	s_waitcnt vmcnt(6)
	v_pk_fma_f32 v[18:19], v[22:23], v[112:113], v[110:111] op_sel_hi:[1,0,1] neg_lo:[1,0,0] neg_hi:[1,0,0]
	v_pk_mul_f32 v[110:111], v[36:37], v[36:37]
	v_add_f32_e32 v46, v105, v46
	v_add_f32_e32 v46, v110, v46
	v_pk_fma_f32 v[22:23], v[20:21], v[112:113], v[108:109] op_sel_hi:[1,0,1] neg_lo:[1,0,0] neg_hi:[1,0,0]
	v_pk_mul_f32 v[108:109], v[32:33], v[32:33]
	v_add_f32_e32 v46, v111, v46
	v_add_f32_e32 v46, v108, v46
	s_waitcnt vmcnt(5)
	v_pk_fma_f32 v[16:17], v[26:27], v[112:113], v[124:125] op_sel_hi:[1,0,1] neg_lo:[1,0,0] neg_hi:[1,0,0]
	v_pk_mul_f32 v[124:125], v[22:23], v[22:23]
	v_add_f32_e32 v46, v109, v46
	v_add_f32_e32 v46, v124, v46
	v_pk_fma_f32 v[20:21], v[24:25], v[112:113], v[122:123] op_sel_hi:[1,0,1] neg_lo:[1,0,0] neg_hi:[1,0,0]
	v_pk_mul_f32 v[122:123], v[18:19], v[18:19]
	v_add_f32_e32 v46, v125, v46
	v_add_f32_e32 v46, v122, v46
	v_pk_mul_f32 v[142:143], v[20:21], v[20:21]
	v_add_f32_e32 v46, v123, v46
	v_add_f32_e32 v46, v142, v46
	s_waitcnt vmcnt(4)
	v_pk_fma_f32 v[14:15], v[30:31], v[112:113], v[128:129] op_sel_hi:[1,0,1] neg_lo:[1,0,0] neg_hi:[1,0,0]
	v_pk_mul_f32 v[128:129], v[16:17], v[16:17]
	v_add_f32_e32 v46, v143, v46
	v_pk_fma_f32 v[28:29], v[28:29], v[112:113], v[126:127] op_sel_hi:[1,0,1] neg_lo:[1,0,0] neg_hi:[1,0,0]
	v_add_f32_e32 v46, v128, v46
	v_pk_mul_f32 v[126:127], v[28:29], v[28:29]
	v_add_f32_e32 v46, v129, v46
	v_add_f32_e32 v46, v126, v46
	v_pk_mul_f32 v[144:145], v[14:15], v[14:15]
	v_add_f32_e32 v46, v127, v46
	s_waitcnt vmcnt(3)
	v_pk_fma_f32 v[26:27], v[0:1], v[112:113], v[130:131] op_sel_hi:[1,0,1] neg_lo:[1,0,0] neg_hi:[1,0,0]
	v_add_f32_e32 v46, v144, v46
	v_pk_mul_f32 v[130:131], v[26:27], v[26:27]
	v_add_f32_e32 v46, v145, v46
	v_pk_fma_f32 v[24:25], v[2:3], v[112:113], v[132:133] op_sel_hi:[1,0,1] neg_lo:[1,0,0] neg_hi:[1,0,0]
	v_add_f32_e32 v46, v130, v46
	v_pk_mul_f32 v[132:133], v[24:25], v[24:25]
	v_add_f32_e32 v46, v131, v46
	s_waitcnt vmcnt(2)
	v_pk_fma_f32 v[2:3], v[6:7], v[112:113], v[136:137] op_sel_hi:[1,0,1] neg_lo:[1,0,0] neg_hi:[1,0,0]
	v_pk_fma_f32 v[6:7], v[4:5], v[112:113], v[134:135] op_sel_hi:[1,0,1] neg_lo:[1,0,0] neg_hi:[1,0,0]
	v_add_f32_e32 v46, v132, v46
	v_pk_mul_f32 v[134:135], v[6:7], v[6:7]
	v_add_f32_e32 v46, v133, v46
	v_add_f32_e32 v46, v134, v46
	v_pk_mul_f32 v[136:137], v[2:3], v[2:3]
	v_add_f32_e32 v46, v135, v46
	s_waitcnt vmcnt(1)
	v_pk_fma_f32 v[4:5], v[8:9], v[112:113], v[138:139] op_sel_hi:[1,0,1] neg_lo:[1,0,0] neg_hi:[1,0,0]
	v_add_f32_e32 v46, v136, v46
	v_pk_mul_f32 v[8:9], v[4:5], v[4:5]
	v_add_f32_e32 v46, v137, v46
	v_pk_fma_f32 v[0:1], v[10:11], v[112:113], v[140:141] op_sel_hi:[1,0,1] neg_lo:[1,0,0] neg_hi:[1,0,0]
	v_add_f32_e32 v8, v8, v46
	v_pk_mul_f32 v[10:11], v[0:1], v[0:1]
	v_add_f32_e32 v8, v9, v8
	v_add_f32_e32 v8, v10, v8
	v_pk_mul_f32 v[30:31], v[68:69], v[68:69]
	v_add_f32_e32 v8, v11, v8
	v_add_f32_e32 v8, v30, v8
	v_pk_mul_f32 v[44:45], v[12:13], v[12:13]
	v_add_f32_e32 v8, v31, v8
	v_add_f32_e32 v8, v44, v8
	v_add_f32_e32 v10, v45, v8
	ds_bpermute_b32 v11, v158, v10
	v_lshl_add_u32 v112, s24, 13, v121
	v_lshlrev_b64 v[8:9], 11, v[112:113]
	v_lshl_add_u64 v[8:9], s[36:37], 0, v[8:9]
	v_lshl_add_u64 v[8:9], v[8:9], 0, s[8:9]
	s_waitcnt lgkmcnt(0)
	v_add_f32_e32 v10, v10, v11
	v_fmamk_f32 v10, v10, 0x3c000000, v193
	v_mul_f32_e32 v11, 0x4b800000, v10
	v_cmp_gt_f32_e32 vcc, s22, v10
	v_mov_b32_e32 v121, v113
	v_lshl_add_u64 v[30:31], v[8:9], 0, v[120:121]
	v_cndmask_b32_e32 v10, v10, v11, vcc
	v_rsq_f32_e32 v10, v10
	s_nop 0
	v_mul_f32_e32 v8, 0x45800000, v10
	v_cndmask_b32_e32 v8, v10, v8, vcc
	v_mul_f32_e32 v44, 0x3f4ccccd, v8
	v_pk_mul_f32 v[8:9], v[72:73], v[44:45] op_sel_hi:[1,0]
	v_pk_mul_f32 v[10:11], v[70:71], v[44:45] op_sel_hi:[1,0]
	s_waitcnt vmcnt(0)
	v_pk_mul_f32 v[8:9], v[64:65], v[8:9]
	v_pk_mul_f32 v[10:11], v[66:67], v[10:11]
	v_cvt_pk_bf16_f32 v8, v8, v9
	v_cvt_pk_bf16_f32 v9, v10, v11
	global_store_dwordx2 v[30:31], v[8:9], off
	global_load_dwordx4 v[220:223], v[116:117], off offset:32
	global_load_dwordx4 v[224:227], v[116:117], off offset:64
	global_load_dwordx4 v[228:231], v[116:117], off offset:96
	global_load_dwordx4 v[232:235], v[116:117], off offset:128
	global_load_dwordx4 v[240:243], v[116:117], off offset:160
	global_load_dwordx4 v[246:249], v[116:117], off offset:192
	global_load_dwordx4 v[250:253], v[116:117], off offset:224
	v_pk_mul_f32 v[46:47], v[76:77], v[44:45] op_sel_hi:[1,0]
	v_pk_mul_f32 v[62:63], v[74:75], v[44:45] op_sel_hi:[1,0]
	v_pk_mul_f32 v[58:59], v[58:59], v[44:45] op_sel_hi:[1,0]
	v_pk_mul_f32 v[54:55], v[54:55], v[44:45] op_sel_hi:[1,0]
	v_pk_mul_f32 v[50:51], v[50:51], v[44:45] op_sel_hi:[1,0]
	v_pk_mul_f32 v[48:49], v[48:49], v[44:45] op_sel_hi:[1,0]
	v_pk_mul_f32 v[42:43], v[42:43], v[44:45] op_sel_hi:[1,0]
	v_pk_mul_f32 v[38:39], v[38:39], v[44:45] op_sel_hi:[1,0]
	v_pk_mul_f32 v[34:35], v[34:35], v[44:45] op_sel_hi:[1,0]
	v_pk_mul_f32 v[32:33], v[32:33], v[44:45] op_sel_hi:[1,0]
	v_pk_mul_f32 v[22:23], v[22:23], v[44:45] op_sel_hi:[1,0]
	v_pk_mul_f32 v[18:19], v[18:19], v[44:45] op_sel_hi:[1,0]
	v_pk_mul_f32 v[16:17], v[16:17], v[44:45] op_sel_hi:[1,0]
	v_pk_mul_f32 v[14:15], v[14:15], v[44:45] op_sel_hi:[1,0]
	v_pk_mul_f32 v[6:7], v[6:7], v[44:45] op_sel_hi:[1,0]
	v_pk_mul_f32 v[2:3], v[2:3], v[44:45] op_sel_hi:[1,0]
	v_pk_mul_f32 v[0:1], v[0:1], v[44:45] op_sel_hi:[1,0]
	s_waitcnt vmcnt(6)
	v_pk_mul_f32 v[220:221], v[220:221], v[46:47]
	v_pk_mul_f32 v[222:223], v[222:223], v[62:63]
	v_cvt_pk_bf16_f32 v220, v220, v221
	v_cvt_pk_bf16_f32 v221, v222, v223
	global_store_dwordx2 v[30:31], v[220:221], off offset:16
	v_pk_mul_f32 v[46:47], v[78:79], v[44:45] op_sel_hi:[1,0]
	s_waitcnt vmcnt(6)
	v_pk_mul_f32 v[226:227], v[226:227], v[58:59]
	v_pk_mul_f32 v[224:225], v[224:225], v[46:47]
	v_pk_mul_f32 v[46:47], v[60:61], v[44:45] op_sel_hi:[1,0]
	v_cvt_pk_bf16_f32 v224, v224, v225
	v_cvt_pk_bf16_f32 v225, v226, v227
	global_store_dwordx2 v[30:31], v[224:225], off offset:32
	s_waitcnt vmcnt(6)
	v_pk_mul_f32 v[228:229], v[228:229], v[46:47]
	v_pk_mul_f32 v[230:231], v[230:231], v[54:55]
	v_cvt_pk_bf16_f32 v228, v228, v229
	v_cvt_pk_bf16_f32 v229, v230, v231
	global_store_dwordx2 v[30:31], v[228:229], off offset:48
	v_pk_mul_f32 v[46:47], v[56:57], v[44:45] op_sel_hi:[1,0]
	s_waitcnt vmcnt(6)
	v_pk_mul_f32 v[234:235], v[234:235], v[50:51]
	v_pk_mul_f32 v[232:233], v[232:233], v[46:47]
	v_pk_mul_f32 v[46:47], v[52:53], v[44:45] op_sel_hi:[1,0]
	v_cvt_pk_bf16_f32 v232, v232, v233
	v_cvt_pk_bf16_f32 v233, v234, v235
	global_store_dwordx2 v[30:31], v[232:233], off offset:64
	s_waitcnt vmcnt(6)
	v_pk_mul_f32 v[240:241], v[240:241], v[46:47]
	v_pk_mul_f32 v[242:243], v[242:243], v[48:49]
	v_cvt_pk_bf16_f32 v240, v240, v241
	v_cvt_pk_bf16_f32 v241, v242, v243
	global_store_dwordx2 v[30:31], v[240:241], off offset:80
	s_waitcnt vmcnt(6)
	v_pk_mul_f32 v[246:247], v[246:247], v[42:43]
	v_pk_mul_f32 v[248:249], v[248:249], v[38:39]
	v_cvt_pk_bf16_f32 v246, v246, v247
	v_cvt_pk_bf16_f32 v247, v248, v249
	global_store_dwordx2 v[30:31], v[246:247], off offset:96
	v_pk_mul_f32 v[38:39], v[40:41], v[44:45] op_sel_hi:[1,0]
	s_waitcnt vmcnt(6)
	v_pk_mul_f32 v[252:253], v[252:253], v[34:35]
	v_pk_mul_f32 v[250:251], v[250:251], v[38:39]
	v_pk_mul_f32 v[34:35], v[36:37], v[44:45] op_sel_hi:[1,0]
	v_cvt_pk_bf16_f32 v250, v250, v251
	v_cvt_pk_bf16_f32 v251, v252, v253
	global_store_dwordx2 v[30:31], v[250:251], off offset:112
	global_load_dwordx4 v[220:223], v[116:117], off offset:256
	global_load_dwordx4 v[224:227], v[116:117], off offset:288
	global_load_dwordx4 v[228:231], v[116:117], off offset:320
	global_load_dwordx4 v[232:235], v[116:117], off offset:352
	global_load_dwordx4 v[240:243], v[116:117], off offset:384
	global_load_dwordx4 v[246:249], v[116:117], off offset:416
	s_waitcnt vmcnt(5)
	v_pk_mul_f32 v[220:221], v[220:221], v[34:35]
	v_pk_mul_f32 v[222:223], v[222:223], v[32:33]
	v_cvt_pk_bf16_f32 v220, v220, v221
	v_cvt_pk_bf16_f32 v221, v222, v223
	global_store_dwordx2 v[30:31], v[220:221], off offset:128
	s_waitcnt vmcnt(5)
	v_pk_mul_f32 v[224:225], v[224:225], v[22:23]
	v_pk_mul_f32 v[226:227], v[226:227], v[18:19]
	v_cvt_pk_bf16_f32 v224, v224, v225
	v_cvt_pk_bf16_f32 v225, v226, v227
	global_store_dwordx2 v[30:31], v[224:225], off offset:144
	v_pk_mul_f32 v[18:19], v[20:21], v[44:45] op_sel_hi:[1,0]
	s_waitcnt vmcnt(5)
	v_pk_mul_f32 v[230:231], v[230:231], v[16:17]
	v_pk_mul_f32 v[228:229], v[228:229], v[18:19]
	v_pk_mul_f32 v[16:17], v[28:29], v[44:45] op_sel_hi:[1,0]
	v_cvt_pk_bf16_f32 v228, v228, v229
	v_cvt_pk_bf16_f32 v229, v230, v231
	global_store_dwordx2 v[30:31], v[228:229], off offset:160
	s_waitcnt vmcnt(5)
	v_pk_mul_f32 v[232:233], v[232:233], v[16:17]
	v_pk_mul_f32 v[234:235], v[234:235], v[14:15]
	v_cvt_pk_bf16_f32 v232, v232, v233
	v_cvt_pk_bf16_f32 v233, v234, v235
	global_store_dwordx2 v[30:31], v[232:233], off offset:176
	v_pk_mul_f32 v[14:15], v[26:27], v[44:45] op_sel_hi:[1,0]
	v_pk_mul_f32 v[16:17], v[24:25], v[44:45] op_sel_hi:[1,0]
	s_waitcnt vmcnt(5)
	v_pk_mul_f32 v[240:241], v[240:241], v[14:15]
	v_pk_mul_f32 v[242:243], v[242:243], v[16:17]
	v_cvt_pk_bf16_f32 v240, v240, v241
	v_cvt_pk_bf16_f32 v241, v242, v243
	global_store_dwordx2 v[30:31], v[240:241], off offset:192
	s_waitcnt vmcnt(5)
	v_pk_mul_f32 v[6:7], v[246:247], v[6:7]
	v_pk_mul_f32 v[2:3], v[248:249], v[2:3]
	v_cvt_pk_bf16_f32 v6, v6, v7
	v_cvt_pk_bf16_f32 v7, v2, v3
	global_store_dwordx2 v[30:31], v[6:7], off offset:208
	global_load_dwordx4 v[6:9], v[116:117], off offset:448
	v_pk_mul_f32 v[2:3], v[4:5], v[44:45] op_sel_hi:[1,0]
	v_pk_mul_f32 v[4:5], v[68:69], v[44:45] op_sel_hi:[1,0]
	s_waitcnt vmcnt(0)
	v_pk_mul_f32 v[2:3], v[6:7], v[2:3]
	v_pk_mul_f32 v[0:1], v[8:9], v[0:1]
	v_cvt_pk_bf16_f32 v2, v2, v3
	v_cvt_pk_bf16_f32 v3, v0, v1
	global_store_dwordx2 v[30:31], v[2:3], off offset:224
	global_load_dwordx4 v[0:3], v[116:117], off offset:480
	v_pk_mul_f32 v[6:7], v[12:13], v[44:45] op_sel_hi:[1,0]
	s_waitcnt vmcnt(0)
	v_pk_mul_f32 v[0:1], v[0:1], v[4:5]
	v_pk_mul_f32 v[2:3], v[2:3], v[6:7]
	v_cvt_pk_bf16_f32 v0, v0, v1
	v_cvt_pk_bf16_f32 v1, v2, v3
	global_store_dwordx2 v[30:31], v[0:1], off offset:240

.Lxg_loop_p12:
	s_waitcnt lgkmcnt(0)
	v_lshl_add_u32 v250, v240, 9, v241
	v_lshl_add_u32 v251, v242, 9, v241
	v_lshl_add_u32 v252, v246, 9, v241
	v_lshl_add_u32 v253, v248, 9, v241
	global_load_dwordx4 v[192:195], v250, s[98:99]
	global_load_dwordx4 v[196:199], v251, s[98:99]
	global_load_dwordx4 v[200:203], v252, s[98:99]
	global_load_dwordx4 v[204:207], v253, s[98:99]
	global_load_dwordx4 v[208:211], v250, s[100:101]
	global_load_dwordx4 v[212:215], v251, s[100:101]
	global_load_dwordx4 v[216:219], v252, s[100:101]
	global_load_dwordx4 v[220:223], v253, s[100:101]
	s_add_u32 s20, s19, 2
	s_cmp_lt_u32 s20, 8
	s_cselect_b64 s[4:5], -1, 0
	s_and_b32 s20, s20, 7
	s_lshl_b32 s20, s20, 5
	v_cndmask_b32_e64 v126, v94, v92, s[4:5]
	v_lshl_add_u32 v129, v136, 2, s20
	ds_bpermute_b32 v240, v129, v126
	ds_bpermute_b32 v242, v129, v126 offset:8
	ds_bpermute_b32 v246, v129, v126 offset:16
	ds_bpermute_b32 v248, v129, v126 offset:24
	s_add_u32 s20, s19, 0
	s_cmp_lt_u32 s20, 8
	s_cselect_b64 s[4:5], -1, 0
	s_and_b32 s20, s20, 7
	s_lshl_b32 s20, s20, 5
	v_cndmask_b32_e64 v127, v147, v146, s[4:5]
	v_cndmask_b32_e64 v128, v149, v148, s[4:5]
	v_lshl_add_u32 v130, v137, 2, s20
	ds_bpermute_b32 v156, v130, v127
	ds_bpermute_b32 v157, v130, v128
	s_waitcnt vmcnt(14)
	v_cvt_scalef32_pk_f32_fp4 v[224:225], v160, 1.0
	v_cvt_scalef32_pk_f32_fp4 v[226:227], v164, 1.0
	v_cvt_scalef32_pk_f32_fp4 v[228:229], v160, 1.0 op_sel:[1,0,0]
	v_cvt_scalef32_pk_f32_fp4 v[230:231], v164, 1.0 op_sel:[1,0,0]
	v_pk_fma_f32 v[232:233], v[24:25], v[224:225], 0 op_sel_hi:[1,1,0]
	v_pk_fma_f32 v[234:235], v[24:25], v[226:227], 0 op_sel_hi:[1,1,0]
	v_cvt_scalef32_pk_f32_fp4 v[224:225], v160, 1.0 op_sel:[0,1,0]
	v_cvt_scalef32_pk_f32_fp4 v[226:227], v164, 1.0 op_sel:[0,1,0]
	v_pk_fma_f32 v[232:233], v[26:27], v[228:229], v[232:233]
	v_pk_fma_f32 v[234:235], v[26:27], v[230:231], v[234:235]
	v_cvt_scalef32_pk_f32_fp4 v[228:229], v160, 1.0 op_sel:[1,1,0]
	v_cvt_scalef32_pk_f32_fp4 v[230:231], v164, 1.0 op_sel:[1,1,0]
	v_pk_fma_f32 v[232:233], v[12:13], v[224:225], v[232:233]
	v_pk_fma_f32 v[234:235], v[12:13], v[226:227], v[234:235]
	v_cvt_scalef32_pk_f32_fp4 v[224:225], v161, 1.0
	v_cvt_scalef32_pk_f32_fp4 v[226:227], v165, 1.0
	v_pk_fma_f32 v[232:233], v[14:15], v[228:229], v[232:233]
	v_pk_fma_f32 v[234:235], v[14:15], v[230:231], v[234:235]
	v_cvt_scalef32_pk_f32_fp4 v[228:229], v161, 1.0 op_sel:[1,0,0]
	v_cvt_scalef32_pk_f32_fp4 v[230:231], v165, 1.0 op_sel:[1,0,0]
	v_pk_fma_f32 v[232:233], v[4:5], v[224:225], v[232:233]
	v_pk_fma_f32 v[234:235], v[4:5], v[226:227], v[234:235]
	v_cvt_scalef32_pk_f32_fp4 v[224:225], v161, 1.0 op_sel:[0,1,0]
	v_cvt_scalef32_pk_f32_fp4 v[226:227], v165, 1.0 op_sel:[0,1,0]
	v_pk_fma_f32 v[232:233], v[6:7], v[228:229], v[232:233]
	v_pk_fma_f32 v[234:235], v[6:7], v[230:231], v[234:235]
	v_cvt_scalef32_pk_f32_fp4 v[228:229], v161, 1.0 op_sel:[1,1,0]
	v_cvt_scalef32_pk_f32_fp4 v[230:231], v165, 1.0 op_sel:[1,1,0]
	v_pk_fma_f32 v[232:233], v[0:1], v[224:225], v[232:233]
	v_pk_fma_f32 v[234:235], v[0:1], v[226:227], v[234:235]
	v_cvt_scalef32_pk_f32_fp4 v[224:225], v162, 1.0
	v_cvt_scalef32_pk_f32_fp4 v[226:227], v166, 1.0
	v_pk_fma_f32 v[232:233], v[2:3], v[228:229], v[232:233]
	v_pk_fma_f32 v[234:235], v[2:3], v[230:231], v[234:235]
	v_cvt_scalef32_pk_f32_fp4 v[228:229], v162, 1.0 op_sel:[1,0,0]
	v_cvt_scalef32_pk_f32_fp4 v[230:231], v166, 1.0 op_sel:[1,0,0]
	v_pk_fma_f32 v[232:233], v[28:29], v[224:225], v[232:233]
	v_pk_fma_f32 v[234:235], v[28:29], v[226:227], v[234:235]
	v_cvt_scalef32_pk_f32_fp4 v[224:225], v162, 1.0 op_sel:[0,1,0]
	v_cvt_scalef32_pk_f32_fp4 v[226:227], v166, 1.0 op_sel:[0,1,0]
	v_pk_fma_f32 v[232:233], v[30:31], v[228:229], v[232:233]
	v_pk_fma_f32 v[234:235], v[30:31], v[230:231], v[234:235]
	v_cvt_scalef32_pk_f32_fp4 v[228:229], v162, 1.0 op_sel:[1,1,0]
	v_cvt_scalef32_pk_f32_fp4 v[230:231], v166, 1.0 op_sel:[1,1,0]
	v_pk_fma_f32 v[232:233], v[16:17], v[224:225], v[232:233]
	v_pk_fma_f32 v[234:235], v[16:17], v[226:227], v[234:235]
	v_cvt_scalef32_pk_f32_fp4 v[224:225], v163, 1.0
	v_cvt_scalef32_pk_f32_fp4 v[226:227], v167, 1.0
	v_pk_fma_f32 v[232:233], v[18:19], v[228:229], v[232:233]
	v_pk_fma_f32 v[234:235], v[18:19], v[230:231], v[234:235]
	v_cvt_scalef32_pk_f32_fp4 v[228:229], v163, 1.0 op_sel:[1,0,0]
	v_cvt_scalef32_pk_f32_fp4 v[230:231], v167, 1.0 op_sel:[1,0,0]
	v_pk_fma_f32 v[232:233], v[8:9], v[224:225], v[232:233]
	v_pk_fma_f32 v[234:235], v[8:9], v[226:227], v[234:235]
	v_cvt_scalef32_pk_f32_fp4 v[224:225], v163, 1.0 op_sel:[0,1,0]
	v_cvt_scalef32_pk_f32_fp4 v[226:227], v167, 1.0 op_sel:[0,1,0]
	v_pk_fma_f32 v[232:233], v[10:11], v[228:229], v[232:233]
	v_pk_fma_f32 v[234:235], v[10:11], v[230:231], v[234:235]
	v_cvt_scalef32_pk_f32_fp4 v[228:229], v163, 1.0 op_sel:[1,1,0]
	v_cvt_scalef32_pk_f32_fp4 v[230:231], v167, 1.0 op_sel:[1,1,0]
	v_pk_fma_f32 v[232:233], v[20:21], v[224:225], v[232:233]
	v_pk_fma_f32 v[234:235], v[20:21], v[226:227], v[234:235]
	v_pk_fma_f32 v[232:233], v[22:23], v[228:229], v[232:233]
	v_pk_fma_f32 v[234:235], v[22:23], v[230:231], v[234:235]
	v_add_f32_e32 v32, v232, v233
	v_add_f32_e32 v33, v234, v235
	s_waitcnt vmcnt(12)
	v_cvt_scalef32_pk_f32_fp4 v[224:225], v168, 1.0
	v_cvt_scalef32_pk_f32_fp4 v[226:227], v172, 1.0
	v_cvt_scalef32_pk_f32_fp4 v[228:229], v168, 1.0 op_sel:[1,0,0]
	v_cvt_scalef32_pk_f32_fp4 v[230:231], v172, 1.0 op_sel:[1,0,0]
	v_pk_fma_f32 v[236:237], v[24:25], v[224:225], 0 op_sel_hi:[1,1,0]
	v_pk_fma_f32 v[238:239], v[24:25], v[226:227], 0 op_sel_hi:[1,1,0]
	v_cvt_scalef32_pk_f32_fp4 v[224:225], v168, 1.0 op_sel:[0,1,0]
	v_cvt_scalef32_pk_f32_fp4 v[226:227], v172, 1.0 op_sel:[0,1,0]
	v_pk_fma_f32 v[236:237], v[26:27], v[228:229], v[236:237]
	v_pk_fma_f32 v[238:239], v[26:27], v[230:231], v[238:239]
	v_cvt_scalef32_pk_f32_fp4 v[228:229], v168, 1.0 op_sel:[1,1,0]
	v_cvt_scalef32_pk_f32_fp4 v[230:231], v172, 1.0 op_sel:[1,1,0]
	v_pk_fma_f32 v[236:237], v[12:13], v[224:225], v[236:237]
	v_pk_fma_f32 v[238:239], v[12:13], v[226:227], v[238:239]
	v_cvt_scalef32_pk_f32_fp4 v[224:225], v169, 1.0
	v_cvt_scalef32_pk_f32_fp4 v[226:227], v173, 1.0
	v_pk_fma_f32 v[236:237], v[14:15], v[228:229], v[236:237]
	v_pk_fma_f32 v[238:239], v[14:15], v[230:231], v[238:239]
	v_cvt_scalef32_pk_f32_fp4 v[228:229], v169, 1.0 op_sel:[1,0,0]
	v_cvt_scalef32_pk_f32_fp4 v[230:231], v173, 1.0 op_sel:[1,0,0]
	v_pk_fma_f32 v[236:237], v[4:5], v[224:225], v[236:237]
	v_pk_fma_f32 v[238:239], v[4:5], v[226:227], v[238:239]
	v_cvt_scalef32_pk_f32_fp4 v[224:225], v169, 1.0 op_sel:[0,1,0]
	v_cvt_scalef32_pk_f32_fp4 v[226:227], v173, 1.0 op_sel:[0,1,0]
	v_pk_fma_f32 v[236:237], v[6:7], v[228:229], v[236:237]
	v_pk_fma_f32 v[238:239], v[6:7], v[230:231], v[238:239]
	v_cvt_scalef32_pk_f32_fp4 v[228:229], v169, 1.0 op_sel:[1,1,0]
	v_cvt_scalef32_pk_f32_fp4 v[230:231], v173, 1.0 op_sel:[1,1,0]
	v_pk_fma_f32 v[236:237], v[0:1], v[224:225], v[236:237]
	v_pk_fma_f32 v[238:239], v[0:1], v[226:227], v[238:239]
	v_cvt_scalef32_pk_f32_fp4 v[224:225], v170, 1.0
	v_cvt_scalef32_pk_f32_fp4 v[226:227], v174, 1.0
	v_pk_fma_f32 v[236:237], v[2:3], v[228:229], v[236:237]
	v_pk_fma_f32 v[238:239], v[2:3], v[230:231], v[238:239]
	v_cvt_scalef32_pk_f32_fp4 v[228:229], v170, 1.0 op_sel:[1,0,0]
	v_cvt_scalef32_pk_f32_fp4 v[230:231], v174, 1.0 op_sel:[1,0,0]
	v_pk_fma_f32 v[236:237], v[28:29], v[224:225], v[236:237]
	v_pk_fma_f32 v[238:239], v[28:29], v[226:227], v[238:239]
	v_cvt_scalef32_pk_f32_fp4 v[224:225], v170, 1.0 op_sel:[0,1,0]
	v_cvt_scalef32_pk_f32_fp4 v[226:227], v174, 1.0 op_sel:[0,1,0]
	v_pk_fma_f32 v[236:237], v[30:31], v[228:229], v[236:237]
	v_pk_fma_f32 v[238:239], v[30:31], v[230:231], v[238:239]
	v_cvt_scalef32_pk_f32_fp4 v[228:229], v170, 1.0 op_sel:[1,1,0]
	v_cvt_scalef32_pk_f32_fp4 v[230:231], v174, 1.0 op_sel:[1,1,0]
	v_pk_fma_f32 v[236:237], v[16:17], v[224:225], v[236:237]
	v_pk_fma_f32 v[238:239], v[16:17], v[226:227], v[238:239]
	v_cvt_scalef32_pk_f32_fp4 v[224:225], v171, 1.0
	v_cvt_scalef32_pk_f32_fp4 v[226:227], v175, 1.0
	v_pk_fma_f32 v[236:237], v[18:19], v[228:229], v[236:237]
	v_pk_fma_f32 v[238:239], v[18:19], v[230:231], v[238:239]
	v_cvt_scalef32_pk_f32_fp4 v[228:229], v171, 1.0 op_sel:[1,0,0]
	v_cvt_scalef32_pk_f32_fp4 v[230:231], v175, 1.0 op_sel:[1,0,0]
	v_pk_fma_f32 v[236:237], v[8:9], v[224:225], v[236:237]
	v_pk_fma_f32 v[238:239], v[8:9], v[226:227], v[238:239]
	v_cvt_scalef32_pk_f32_fp4 v[224:225], v171, 1.0 op_sel:[0,1,0]
	v_cvt_scalef32_pk_f32_fp4 v[226:227], v175, 1.0 op_sel:[0,1,0]
	v_pk_fma_f32 v[236:237], v[10:11], v[228:229], v[236:237]
	v_pk_fma_f32 v[238:239], v[10:11], v[230:231], v[238:239]
	v_cvt_scalef32_pk_f32_fp4 v[228:229], v171, 1.0 op_sel:[1,1,0]
	v_cvt_scalef32_pk_f32_fp4 v[230:231], v175, 1.0 op_sel:[1,1,0]
	v_pk_fma_f32 v[236:237], v[20:21], v[224:225], v[236:237]
	v_pk_fma_f32 v[238:239], v[20:21], v[226:227], v[238:239]
	v_pk_fma_f32 v[236:237], v[22:23], v[228:229], v[236:237]
	v_pk_fma_f32 v[238:239], v[22:23], v[230:231], v[238:239]
	v_add_f32_e32 v34, v236, v237
	v_add_f32_e32 v35, v238, v239
	s_nop 1
	v_permlane16_swap_b32_e32 v32, v34
	v_permlane16_swap_b32_e32 v33, v35
	v_add_f32_e32 v36, v32, v34
	v_add_f32_e32 v38, v33, v35
	s_waitcnt lgkmcnt(0)
	v_cndmask_b32_e64 v40, v38, v36, s[0:1]
	v_cndmask_b32_e64 v41, v36, v38, s[0:1]
	s_nop 1
	v_add_f32_dpp v40, v41, v40 row_ror:8 row_mask:0xf bank_mask:0xf
	s_nop 1
	v_add_f32_dpp v40, v40, v40 quad_perm:[1,0,3,2] row_mask:0xf bank_mask:0xf
	s_nop 1
	v_add_f32_dpp v40, v40, v40 quad_perm:[2,3,0,1] row_mask:0xf bank_mask:0xf
	s_nop 1
	v_add_f32_dpp v40, v40, v40 row_half_mirror row_mask:0xf bank_mask:0xf
	v_mul_f32_e32 v42, v40, v156
	v_fma_f32 v43, |v42|, s16, 1.0
	v_rcp_f32_e32 v43, v43
	v_cmp_gt_f32_e64 s[4:5], 0, v42
	v_mul_f32_e32 v45, v42, v42
	v_fmamk_f32 v44, v43, 0x3f07dc22, v142
	v_fmaak_f32 v44, v43, v44, 0x3f35f0e3
	v_fmaak_f32 v44, v43, v44, 0xbe11a98e
	v_fmaak_f32 v44, v43, v44, 0x3e027906
	v_mul_f32_e32 v45, 0xbf38aa3b, v45
	v_exp_f32_e32 v45, v45
	v_mul_f32_e32 v43, v43, v44
	v_mul_f32_e32 v43, v45, v43
	v_mul_f32_e32 v44, v42, v43
	v_fma_f32 v42, -v42, v43, v42
	v_cndmask_b32_e64 v42, v42, v44, s[4:5]
	v_mul_f32_e32 v158, v42, v157
	ds_bpermute_b32 v118, v138, v158
	ds_bpermute_b32 v120, v139, v158
	ds_bpermute_b32 v122, v140, v158
	ds_bpermute_b32 v124, v141, v158
	s_waitcnt vmcnt(11)
	v_cvt_scalef32_pk_f32_fp4 v[224:225], v176, 1.0
	v_cvt_scalef32_pk_f32_fp4 v[226:227], v176, 1.0 op_sel:[1,0,0]
	s_waitcnt lgkmcnt(0)
	v_cvt_scalef32_pk_f32_fp4 v[228:229], v176, 1.0 op_sel:[0,1,0]
	v_pk_fma_f32 v[112:113], v[224:225], v[118:119], v[112:113] op_sel_hi:[1,0,1]
	v_cvt_scalef32_pk_f32_fp4 v[230:231], v176, 1.0 op_sel:[1,1,0]
	v_pk_fma_f32 v[108:109], v[226:227], v[118:119], v[108:109] op_sel_hi:[1,0,1]
	v_cvt_scalef32_pk_f32_fp4 v[224:225], v177, 1.0
	v_pk_fma_f32 v[104:105], v[228:229], v[118:119], v[104:105] op_sel_hi:[1,0,1]
	v_cvt_scalef32_pk_f32_fp4 v[226:227], v177, 1.0 op_sel:[1,0,0]
	v_pk_fma_f32 v[98:99], v[230:231], v[118:119], v[98:99] op_sel_hi:[1,0,1]
	v_cvt_scalef32_pk_f32_fp4 v[228:229], v177, 1.0 op_sel:[0,1,0]
	v_pk_fma_f32 v[54:55], v[224:225], v[118:119], v[54:55] op_sel_hi:[1,0,1]
	v_cvt_scalef32_pk_f32_fp4 v[230:231], v177, 1.0 op_sel:[1,1,0]
	v_pk_fma_f32 v[58:59], v[226:227], v[118:119], v[58:59] op_sel_hi:[1,0,1]
	v_cvt_scalef32_pk_f32_fp4 v[224:225], v178, 1.0
	v_pk_fma_f32 v[52:53], v[228:229], v[118:119], v[52:53] op_sel_hi:[1,0,1]
	v_cvt_scalef32_pk_f32_fp4 v[226:227], v178, 1.0 op_sel:[1,0,0]
	v_pk_fma_f32 v[48:49], v[230:231], v[118:119], v[48:49] op_sel_hi:[1,0,1]
	v_cvt_scalef32_pk_f32_fp4 v[228:229], v178, 1.0 op_sel:[0,1,0]
	v_pk_fma_f32 v[106:107], v[224:225], v[118:119], v[106:107] op_sel_hi:[1,0,1]
	v_cvt_scalef32_pk_f32_fp4 v[230:231], v178, 1.0 op_sel:[1,1,0]
	v_pk_fma_f32 v[102:103], v[226:227], v[118:119], v[102:103] op_sel_hi:[1,0,1]
	v_cvt_scalef32_pk_f32_fp4 v[224:225], v179, 1.0
	v_pk_fma_f32 v[96:97], v[228:229], v[118:119], v[96:97] op_sel_hi:[1,0,1]
	v_cvt_scalef32_pk_f32_fp4 v[226:227], v179, 1.0 op_sel:[1,0,0]
	v_pk_fma_f32 v[56:57], v[230:231], v[118:119], v[56:57] op_sel_hi:[1,0,1]
	v_cvt_scalef32_pk_f32_fp4 v[228:229], v179, 1.0 op_sel:[0,1,0]
	v_pk_fma_f32 v[50:51], v[224:225], v[118:119], v[50:51] op_sel_hi:[1,0,1]
	v_cvt_scalef32_pk_f32_fp4 v[230:231], v179, 1.0 op_sel:[1,1,0]
	v_pk_fma_f32 v[114:115], v[226:227], v[118:119], v[114:115] op_sel_hi:[1,0,1]
	v_pk_fma_f32 v[110:111], v[228:229], v[118:119], v[110:111] op_sel_hi:[1,0,1]
	v_pk_fma_f32 v[100:101], v[230:231], v[118:119], v[100:101] op_sel_hi:[1,0,1]
	s_waitcnt vmcnt(10)
	v_cvt_scalef32_pk_f32_fp4 v[224:225], v180, 1.0
	v_cvt_scalef32_pk_f32_fp4 v[226:227], v180, 1.0 op_sel:[1,0,0]
	v_cvt_scalef32_pk_f32_fp4 v[228:229], v180, 1.0 op_sel:[0,1,0]
	v_pk_fma_f32 v[112:113], v[224:225], v[120:121], v[112:113] op_sel_hi:[1,0,1]
	v_cvt_scalef32_pk_f32_fp4 v[230:231], v180, 1.0 op_sel:[1,1,0]
	v_pk_fma_f32 v[108:109], v[226:227], v[120:121], v[108:109] op_sel_hi:[1,0,1]
	v_cvt_scalef32_pk_f32_fp4 v[224:225], v181, 1.0
	v_pk_fma_f32 v[104:105], v[228:229], v[120:121], v[104:105] op_sel_hi:[1,0,1]
	v_cvt_scalef32_pk_f32_fp4 v[226:227], v181, 1.0 op_sel:[1,0,0]
	v_pk_fma_f32 v[98:99], v[230:231], v[120:121], v[98:99] op_sel_hi:[1,0,1]
	v_cvt_scalef32_pk_f32_fp4 v[228:229], v181, 1.0 op_sel:[0,1,0]
	v_pk_fma_f32 v[54:55], v[224:225], v[120:121], v[54:55] op_sel_hi:[1,0,1]
	v_cvt_scalef32_pk_f32_fp4 v[230:231], v181, 1.0 op_sel:[1,1,0]
	v_pk_fma_f32 v[58:59], v[226:227], v[120:121], v[58:59] op_sel_hi:[1,0,1]
	v_cvt_scalef32_pk_f32_fp4 v[224:225], v182, 1.0
	v_pk_fma_f32 v[52:53], v[228:229], v[120:121], v[52:53] op_sel_hi:[1,0,1]
	v_cvt_scalef32_pk_f32_fp4 v[226:227], v182, 1.0 op_sel:[1,0,0]
	v_pk_fma_f32 v[48:49], v[230:231], v[120:121], v[48:49] op_sel_hi:[1,0,1]
	v_cvt_scalef32_pk_f32_fp4 v[228:229], v182, 1.0 op_sel:[0,1,0]
	v_pk_fma_f32 v[106:107], v[224:225], v[120:121], v[106:107] op_sel_hi:[1,0,1]
	v_cvt_scalef32_pk_f32_fp4 v[230:231], v182, 1.0 op_sel:[1,1,0]
	v_pk_fma_f32 v[102:103], v[226:227], v[120:121], v[102:103] op_sel_hi:[1,0,1]
	v_cvt_scalef32_pk_f32_fp4 v[224:225], v183, 1.0
	v_pk_fma_f32 v[96:97], v[228:229], v[120:121], v[96:97] op_sel_hi:[1,0,1]
	v_cvt_scalef32_pk_f32_fp4 v[226:227], v183, 1.0 op_sel:[1,0,0]
	v_pk_fma_f32 v[56:57], v[230:231], v[120:121], v[56:57] op_sel_hi:[1,0,1]
	v_cvt_scalef32_pk_f32_fp4 v[228:229], v183, 1.0 op_sel:[0,1,0]
	v_pk_fma_f32 v[50:51], v[224:225], v[120:121], v[50:51] op_sel_hi:[1,0,1]
	v_cvt_scalef32_pk_f32_fp4 v[230:231], v183, 1.0 op_sel:[1,1,0]
	v_pk_fma_f32 v[114:115], v[226:227], v[120:121], v[114:115] op_sel_hi:[1,0,1]
	v_pk_fma_f32 v[110:111], v[228:229], v[120:121], v[110:111] op_sel_hi:[1,0,1]
	v_pk_fma_f32 v[100:101], v[230:231], v[120:121], v[100:101] op_sel_hi:[1,0,1]
	s_waitcnt vmcnt(9)
	v_cvt_scalef32_pk_f32_fp4 v[224:225], v184, 1.0
	v_cvt_scalef32_pk_f32_fp4 v[226:227], v184, 1.0 op_sel:[1,0,0]
	v_cvt_scalef32_pk_f32_fp4 v[228:229], v184, 1.0 op_sel:[0,1,0]
	v_pk_fma_f32 v[112:113], v[224:225], v[122:123], v[112:113] op_sel_hi:[1,0,1]
	v_cvt_scalef32_pk_f32_fp4 v[230:231], v184, 1.0 op_sel:[1,1,0]
	v_pk_fma_f32 v[108:109], v[226:227], v[122:123], v[108:109] op_sel_hi:[1,0,1]
	v_cvt_scalef32_pk_f32_fp4 v[224:225], v185, 1.0
	v_pk_fma_f32 v[104:105], v[228:229], v[122:123], v[104:105] op_sel_hi:[1,0,1]
	v_cvt_scalef32_pk_f32_fp4 v[226:227], v185, 1.0 op_sel:[1,0,0]
	v_pk_fma_f32 v[98:99], v[230:231], v[122:123], v[98:99] op_sel_hi:[1,0,1]
	v_cvt_scalef32_pk_f32_fp4 v[228:229], v185, 1.0 op_sel:[0,1,0]
	v_pk_fma_f32 v[54:55], v[224:225], v[122:123], v[54:55] op_sel_hi:[1,0,1]
	v_cvt_scalef32_pk_f32_fp4 v[230:231], v185, 1.0 op_sel:[1,1,0]
	v_pk_fma_f32 v[58:59], v[226:227], v[122:123], v[58:59] op_sel_hi:[1,0,1]
	v_cvt_scalef32_pk_f32_fp4 v[224:225], v186, 1.0
	v_pk_fma_f32 v[52:53], v[228:229], v[122:123], v[52:53] op_sel_hi:[1,0,1]
	v_cvt_scalef32_pk_f32_fp4 v[226:227], v186, 1.0 op_sel:[1,0,0]
	v_pk_fma_f32 v[48:49], v[230:231], v[122:123], v[48:49] op_sel_hi:[1,0,1]
	v_cvt_scalef32_pk_f32_fp4 v[228:229], v186, 1.0 op_sel:[0,1,0]
	v_pk_fma_f32 v[106:107], v[224:225], v[122:123], v[106:107] op_sel_hi:[1,0,1]
	v_cvt_scalef32_pk_f32_fp4 v[230:231], v186, 1.0 op_sel:[1,1,0]
	v_pk_fma_f32 v[102:103], v[226:227], v[122:123], v[102:103] op_sel_hi:[1,0,1]
	v_cvt_scalef32_pk_f32_fp4 v[224:225], v187, 1.0
	v_pk_fma_f32 v[96:97], v[228:229], v[122:123], v[96:97] op_sel_hi:[1,0,1]
	v_cvt_scalef32_pk_f32_fp4 v[226:227], v187, 1.0 op_sel:[1,0,0]
	v_pk_fma_f32 v[56:57], v[230:231], v[122:123], v[56:57] op_sel_hi:[1,0,1]
	v_cvt_scalef32_pk_f32_fp4 v[228:229], v187, 1.0 op_sel:[0,1,0]
	v_pk_fma_f32 v[50:51], v[224:225], v[122:123], v[50:51] op_sel_hi:[1,0,1]
	v_cvt_scalef32_pk_f32_fp4 v[230:231], v187, 1.0 op_sel:[1,1,0]
	v_pk_fma_f32 v[114:115], v[226:227], v[122:123], v[114:115] op_sel_hi:[1,0,1]
	v_pk_fma_f32 v[110:111], v[228:229], v[122:123], v[110:111] op_sel_hi:[1,0,1]
	v_pk_fma_f32 v[100:101], v[230:231], v[122:123], v[100:101] op_sel_hi:[1,0,1]
	s_waitcnt vmcnt(8)
	v_cvt_scalef32_pk_f32_fp4 v[224:225], v188, 1.0
	v_cvt_scalef32_pk_f32_fp4 v[226:227], v188, 1.0 op_sel:[1,0,0]
	v_cvt_scalef32_pk_f32_fp4 v[228:229], v188, 1.0 op_sel:[0,1,0]
	v_pk_fma_f32 v[112:113], v[224:225], v[124:125], v[112:113] op_sel_hi:[1,0,1]
	v_cvt_scalef32_pk_f32_fp4 v[230:231], v188, 1.0 op_sel:[1,1,0]
	v_pk_fma_f32 v[108:109], v[226:227], v[124:125], v[108:109] op_sel_hi:[1,0,1]
	v_cvt_scalef32_pk_f32_fp4 v[224:225], v189, 1.0
	v_pk_fma_f32 v[104:105], v[228:229], v[124:125], v[104:105] op_sel_hi:[1,0,1]
	v_cvt_scalef32_pk_f32_fp4 v[226:227], v189, 1.0 op_sel:[1,0,0]
	v_pk_fma_f32 v[98:99], v[230:231], v[124:125], v[98:99] op_sel_hi:[1,0,1]
	v_cvt_scalef32_pk_f32_fp4 v[228:229], v189, 1.0 op_sel:[0,1,0]
	v_pk_fma_f32 v[54:55], v[224:225], v[124:125], v[54:55] op_sel_hi:[1,0,1]
	v_cvt_scalef32_pk_f32_fp4 v[230:231], v189, 1.0 op_sel:[1,1,0]
	v_pk_fma_f32 v[58:59], v[226:227], v[124:125], v[58:59] op_sel_hi:[1,0,1]
	v_cvt_scalef32_pk_f32_fp4 v[224:225], v190, 1.0
	v_pk_fma_f32 v[52:53], v[228:229], v[124:125], v[52:53] op_sel_hi:[1,0,1]
	v_cvt_scalef32_pk_f32_fp4 v[226:227], v190, 1.0 op_sel:[1,0,0]
	v_pk_fma_f32 v[48:49], v[230:231], v[124:125], v[48:49] op_sel_hi:[1,0,1]
	v_cvt_scalef32_pk_f32_fp4 v[228:229], v190, 1.0 op_sel:[0,1,0]
	v_pk_fma_f32 v[106:107], v[224:225], v[124:125], v[106:107] op_sel_hi:[1,0,1]
	v_cvt_scalef32_pk_f32_fp4 v[230:231], v190, 1.0 op_sel:[1,1,0]
	v_pk_fma_f32 v[102:103], v[226:227], v[124:125], v[102:103] op_sel_hi:[1,0,1]
	v_cvt_scalef32_pk_f32_fp4 v[224:225], v191, 1.0
	v_pk_fma_f32 v[96:97], v[228:229], v[124:125], v[96:97] op_sel_hi:[1,0,1]
	v_cvt_scalef32_pk_f32_fp4 v[226:227], v191, 1.0 op_sel:[1,0,0]
	v_pk_fma_f32 v[56:57], v[230:231], v[124:125], v[56:57] op_sel_hi:[1,0,1]
	v_cvt_scalef32_pk_f32_fp4 v[228:229], v191, 1.0 op_sel:[0,1,0]
	v_pk_fma_f32 v[50:51], v[224:225], v[124:125], v[50:51] op_sel_hi:[1,0,1]
	v_cvt_scalef32_pk_f32_fp4 v[230:231], v191, 1.0 op_sel:[1,1,0]
	v_pk_fma_f32 v[114:115], v[226:227], v[124:125], v[114:115] op_sel_hi:[1,0,1]
	v_pk_fma_f32 v[110:111], v[228:229], v[124:125], v[110:111] op_sel_hi:[1,0,1]
	v_pk_fma_f32 v[100:101], v[230:231], v[124:125], v[100:101] op_sel_hi:[1,0,1]
	s_waitcnt lgkmcnt(0)
	v_lshl_add_u32 v250, v240, 9, v241
	v_lshl_add_u32 v251, v242, 9, v241
	v_lshl_add_u32 v252, v246, 9, v241
	v_lshl_add_u32 v253, v248, 9, v241
	global_load_dwordx4 v[160:163], v250, s[98:99]
	global_load_dwordx4 v[164:167], v251, s[98:99]
	global_load_dwordx4 v[168:171], v252, s[98:99]
	global_load_dwordx4 v[172:175], v253, s[98:99]
	global_load_dwordx4 v[176:179], v250, s[100:101]
	global_load_dwordx4 v[180:183], v251, s[100:101]
	global_load_dwordx4 v[184:187], v252, s[100:101]
	global_load_dwordx4 v[188:191], v253, s[100:101]
	s_add_u32 s20, s19, 3
	s_cmp_lt_u32 s20, 8
	s_cselect_b64 s[4:5], -1, 0
	s_and_b32 s20, s20, 7
	s_lshl_b32 s20, s20, 5
	v_cndmask_b32_e64 v126, v94, v92, s[4:5]
	v_lshl_add_u32 v129, v136, 2, s20
	ds_bpermute_b32 v240, v129, v126
	ds_bpermute_b32 v242, v129, v126 offset:8
	ds_bpermute_b32 v246, v129, v126 offset:16
	ds_bpermute_b32 v248, v129, v126 offset:24
	s_add_u32 s20, s19, 1
	s_cmp_lt_u32 s20, 8
	s_cselect_b64 s[4:5], -1, 0
	s_and_b32 s20, s20, 7
	s_lshl_b32 s20, s20, 5
	v_cndmask_b32_e64 v127, v147, v146, s[4:5]
	v_cndmask_b32_e64 v128, v149, v148, s[4:5]
	v_lshl_add_u32 v130, v137, 2, s20
	ds_bpermute_b32 v156, v130, v127
	ds_bpermute_b32 v157, v130, v128
	s_waitcnt vmcnt(14)
	v_cvt_scalef32_pk_f32_fp4 v[224:225], v192, 1.0
	v_cvt_scalef32_pk_f32_fp4 v[226:227], v196, 1.0
	v_cvt_scalef32_pk_f32_fp4 v[228:229], v192, 1.0 op_sel:[1,0,0]
	v_cvt_scalef32_pk_f32_fp4 v[230:231], v196, 1.0 op_sel:[1,0,0]
	v_pk_fma_f32 v[232:233], v[24:25], v[224:225], 0 op_sel_hi:[1,1,0]
	v_pk_fma_f32 v[234:235], v[24:25], v[226:227], 0 op_sel_hi:[1,1,0]
	v_cvt_scalef32_pk_f32_fp4 v[224:225], v192, 1.0 op_sel:[0,1,0]
	v_cvt_scalef32_pk_f32_fp4 v[226:227], v196, 1.0 op_sel:[0,1,0]
	v_pk_fma_f32 v[232:233], v[26:27], v[228:229], v[232:233]
	v_pk_fma_f32 v[234:235], v[26:27], v[230:231], v[234:235]
	v_cvt_scalef32_pk_f32_fp4 v[228:229], v192, 1.0 op_sel:[1,1,0]
	v_cvt_scalef32_pk_f32_fp4 v[230:231], v196, 1.0 op_sel:[1,1,0]
	v_pk_fma_f32 v[232:233], v[12:13], v[224:225], v[232:233]
	v_pk_fma_f32 v[234:235], v[12:13], v[226:227], v[234:235]
	v_cvt_scalef32_pk_f32_fp4 v[224:225], v193, 1.0
	v_cvt_scalef32_pk_f32_fp4 v[226:227], v197, 1.0
	v_pk_fma_f32 v[232:233], v[14:15], v[228:229], v[232:233]
	v_pk_fma_f32 v[234:235], v[14:15], v[230:231], v[234:235]
	v_cvt_scalef32_pk_f32_fp4 v[228:229], v193, 1.0 op_sel:[1,0,0]
	v_cvt_scalef32_pk_f32_fp4 v[230:231], v197, 1.0 op_sel:[1,0,0]
	v_pk_fma_f32 v[232:233], v[4:5], v[224:225], v[232:233]
	v_pk_fma_f32 v[234:235], v[4:5], v[226:227], v[234:235]
	v_cvt_scalef32_pk_f32_fp4 v[224:225], v193, 1.0 op_sel:[0,1,0]
	v_cvt_scalef32_pk_f32_fp4 v[226:227], v197, 1.0 op_sel:[0,1,0]
	v_pk_fma_f32 v[232:233], v[6:7], v[228:229], v[232:233]
	v_pk_fma_f32 v[234:235], v[6:7], v[230:231], v[234:235]
	v_cvt_scalef32_pk_f32_fp4 v[228:229], v193, 1.0 op_sel:[1,1,0]
	v_cvt_scalef32_pk_f32_fp4 v[230:231], v197, 1.0 op_sel:[1,1,0]
	v_pk_fma_f32 v[232:233], v[0:1], v[224:225], v[232:233]
	v_pk_fma_f32 v[234:235], v[0:1], v[226:227], v[234:235]
	v_cvt_scalef32_pk_f32_fp4 v[224:225], v194, 1.0
	v_cvt_scalef32_pk_f32_fp4 v[226:227], v198, 1.0
	v_pk_fma_f32 v[232:233], v[2:3], v[228:229], v[232:233]
	v_pk_fma_f32 v[234:235], v[2:3], v[230:231], v[234:235]
	v_cvt_scalef32_pk_f32_fp4 v[228:229], v194, 1.0 op_sel:[1,0,0]
	v_cvt_scalef32_pk_f32_fp4 v[230:231], v198, 1.0 op_sel:[1,0,0]
	v_pk_fma_f32 v[232:233], v[28:29], v[224:225], v[232:233]
	v_pk_fma_f32 v[234:235], v[28:29], v[226:227], v[234:235]
	v_cvt_scalef32_pk_f32_fp4 v[224:225], v194, 1.0 op_sel:[0,1,0]
	v_cvt_scalef32_pk_f32_fp4 v[226:227], v198, 1.0 op_sel:[0,1,0]
	v_pk_fma_f32 v[232:233], v[30:31], v[228:229], v[232:233]
	v_pk_fma_f32 v[234:235], v[30:31], v[230:231], v[234:235]
	v_cvt_scalef32_pk_f32_fp4 v[228:229], v194, 1.0 op_sel:[1,1,0]
	v_cvt_scalef32_pk_f32_fp4 v[230:231], v198, 1.0 op_sel:[1,1,0]
	v_pk_fma_f32 v[232:233], v[16:17], v[224:225], v[232:233]
	v_pk_fma_f32 v[234:235], v[16:17], v[226:227], v[234:235]
	v_cvt_scalef32_pk_f32_fp4 v[224:225], v195, 1.0
	v_cvt_scalef32_pk_f32_fp4 v[226:227], v199, 1.0
	v_pk_fma_f32 v[232:233], v[18:19], v[228:229], v[232:233]
	v_pk_fma_f32 v[234:235], v[18:19], v[230:231], v[234:235]
	v_cvt_scalef32_pk_f32_fp4 v[228:229], v195, 1.0 op_sel:[1,0,0]
	v_cvt_scalef32_pk_f32_fp4 v[230:231], v199, 1.0 op_sel:[1,0,0]
	v_pk_fma_f32 v[232:233], v[8:9], v[224:225], v[232:233]
	v_pk_fma_f32 v[234:235], v[8:9], v[226:227], v[234:235]
	v_cvt_scalef32_pk_f32_fp4 v[224:225], v195, 1.0 op_sel:[0,1,0]
	v_cvt_scalef32_pk_f32_fp4 v[226:227], v199, 1.0 op_sel:[0,1,0]
	v_pk_fma_f32 v[232:233], v[10:11], v[228:229], v[232:233]
	v_pk_fma_f32 v[234:235], v[10:11], v[230:231], v[234:235]
	v_cvt_scalef32_pk_f32_fp4 v[228:229], v195, 1.0 op_sel:[1,1,0]
	v_cvt_scalef32_pk_f32_fp4 v[230:231], v199, 1.0 op_sel:[1,1,0]
	v_pk_fma_f32 v[232:233], v[20:21], v[224:225], v[232:233]
	v_pk_fma_f32 v[234:235], v[20:21], v[226:227], v[234:235]
	v_pk_fma_f32 v[232:233], v[22:23], v[228:229], v[232:233]
	v_pk_fma_f32 v[234:235], v[22:23], v[230:231], v[234:235]
	v_add_f32_e32 v32, v232, v233
	v_add_f32_e32 v33, v234, v235
	s_waitcnt vmcnt(12)
	v_cvt_scalef32_pk_f32_fp4 v[224:225], v200, 1.0
	v_cvt_scalef32_pk_f32_fp4 v[226:227], v204, 1.0
	v_cvt_scalef32_pk_f32_fp4 v[228:229], v200, 1.0 op_sel:[1,0,0]
	v_cvt_scalef32_pk_f32_fp4 v[230:231], v204, 1.0 op_sel:[1,0,0]
	v_pk_fma_f32 v[236:237], v[24:25], v[224:225], 0 op_sel_hi:[1,1,0]
	v_pk_fma_f32 v[238:239], v[24:25], v[226:227], 0 op_sel_hi:[1,1,0]
	v_cvt_scalef32_pk_f32_fp4 v[224:225], v200, 1.0 op_sel:[0,1,0]
	v_cvt_scalef32_pk_f32_fp4 v[226:227], v204, 1.0 op_sel:[0,1,0]
	v_pk_fma_f32 v[236:237], v[26:27], v[228:229], v[236:237]
	v_pk_fma_f32 v[238:239], v[26:27], v[230:231], v[238:239]
	v_cvt_scalef32_pk_f32_fp4 v[228:229], v200, 1.0 op_sel:[1,1,0]
	v_cvt_scalef32_pk_f32_fp4 v[230:231], v204, 1.0 op_sel:[1,1,0]
	v_pk_fma_f32 v[236:237], v[12:13], v[224:225], v[236:237]
	v_pk_fma_f32 v[238:239], v[12:13], v[226:227], v[238:239]
	v_cvt_scalef32_pk_f32_fp4 v[224:225], v201, 1.0
	v_cvt_scalef32_pk_f32_fp4 v[226:227], v205, 1.0
	v_pk_fma_f32 v[236:237], v[14:15], v[228:229], v[236:237]
	v_pk_fma_f32 v[238:239], v[14:15], v[230:231], v[238:239]
	v_cvt_scalef32_pk_f32_fp4 v[228:229], v201, 1.0 op_sel:[1,0,0]
	v_cvt_scalef32_pk_f32_fp4 v[230:231], v205, 1.0 op_sel:[1,0,0]
	v_pk_fma_f32 v[236:237], v[4:5], v[224:225], v[236:237]
	v_pk_fma_f32 v[238:239], v[4:5], v[226:227], v[238:239]
	v_cvt_scalef32_pk_f32_fp4 v[224:225], v201, 1.0 op_sel:[0,1,0]
	v_cvt_scalef32_pk_f32_fp4 v[226:227], v205, 1.0 op_sel:[0,1,0]
	v_pk_fma_f32 v[236:237], v[6:7], v[228:229], v[236:237]
	v_pk_fma_f32 v[238:239], v[6:7], v[230:231], v[238:239]
	v_cvt_scalef32_pk_f32_fp4 v[228:229], v201, 1.0 op_sel:[1,1,0]
	v_cvt_scalef32_pk_f32_fp4 v[230:231], v205, 1.0 op_sel:[1,1,0]
	v_pk_fma_f32 v[236:237], v[0:1], v[224:225], v[236:237]
	v_pk_fma_f32 v[238:239], v[0:1], v[226:227], v[238:239]
	v_cvt_scalef32_pk_f32_fp4 v[224:225], v202, 1.0
	v_cvt_scalef32_pk_f32_fp4 v[226:227], v206, 1.0
	v_pk_fma_f32 v[236:237], v[2:3], v[228:229], v[236:237]
	v_pk_fma_f32 v[238:239], v[2:3], v[230:231], v[238:239]
	v_cvt_scalef32_pk_f32_fp4 v[228:229], v202, 1.0 op_sel:[1,0,0]
	v_cvt_scalef32_pk_f32_fp4 v[230:231], v206, 1.0 op_sel:[1,0,0]
	v_pk_fma_f32 v[236:237], v[28:29], v[224:225], v[236:237]
	v_pk_fma_f32 v[238:239], v[28:29], v[226:227], v[238:239]
	v_cvt_scalef32_pk_f32_fp4 v[224:225], v202, 1.0 op_sel:[0,1,0]
	v_cvt_scalef32_pk_f32_fp4 v[226:227], v206, 1.0 op_sel:[0,1,0]
	v_pk_fma_f32 v[236:237], v[30:31], v[228:229], v[236:237]
	v_pk_fma_f32 v[238:239], v[30:31], v[230:231], v[238:239]
	v_cvt_scalef32_pk_f32_fp4 v[228:229], v202, 1.0 op_sel:[1,1,0]
	v_cvt_scalef32_pk_f32_fp4 v[230:231], v206, 1.0 op_sel:[1,1,0]
	v_pk_fma_f32 v[236:237], v[16:17], v[224:225], v[236:237]
	v_pk_fma_f32 v[238:239], v[16:17], v[226:227], v[238:239]
	v_cvt_scalef32_pk_f32_fp4 v[224:225], v203, 1.0
	v_cvt_scalef32_pk_f32_fp4 v[226:227], v207, 1.0
	v_pk_fma_f32 v[236:237], v[18:19], v[228:229], v[236:237]
	v_pk_fma_f32 v[238:239], v[18:19], v[230:231], v[238:239]
	v_cvt_scalef32_pk_f32_fp4 v[228:229], v203, 1.0 op_sel:[1,0,0]
	v_cvt_scalef32_pk_f32_fp4 v[230:231], v207, 1.0 op_sel:[1,0,0]
	v_pk_fma_f32 v[236:237], v[8:9], v[224:225], v[236:237]
	v_pk_fma_f32 v[238:239], v[8:9], v[226:227], v[238:239]
	v_cvt_scalef32_pk_f32_fp4 v[224:225], v203, 1.0 op_sel:[0,1,0]
	v_cvt_scalef32_pk_f32_fp4 v[226:227], v207, 1.0 op_sel:[0,1,0]
	v_pk_fma_f32 v[236:237], v[10:11], v[228:229], v[236:237]
	v_pk_fma_f32 v[238:239], v[10:11], v[230:231], v[238:239]
	v_cvt_scalef32_pk_f32_fp4 v[228:229], v203, 1.0 op_sel:[1,1,0]
	v_cvt_scalef32_pk_f32_fp4 v[230:231], v207, 1.0 op_sel:[1,1,0]
	v_pk_fma_f32 v[236:237], v[20:21], v[224:225], v[236:237]
	v_pk_fma_f32 v[238:239], v[20:21], v[226:227], v[238:239]
	v_pk_fma_f32 v[236:237], v[22:23], v[228:229], v[236:237]
	v_pk_fma_f32 v[238:239], v[22:23], v[230:231], v[238:239]
	v_add_f32_e32 v34, v236, v237
	v_add_f32_e32 v35, v238, v239
	s_nop 1
	v_permlane16_swap_b32_e32 v32, v34
	v_permlane16_swap_b32_e32 v33, v35
	v_add_f32_e32 v36, v32, v34
	v_add_f32_e32 v38, v33, v35
	s_waitcnt lgkmcnt(0)
	v_cndmask_b32_e64 v40, v38, v36, s[0:1]
	v_cndmask_b32_e64 v41, v36, v38, s[0:1]
	s_nop 1
	v_add_f32_dpp v40, v41, v40 row_ror:8 row_mask:0xf bank_mask:0xf
	s_nop 1
	v_add_f32_dpp v40, v40, v40 quad_perm:[1,0,3,2] row_mask:0xf bank_mask:0xf
	s_nop 1
	v_add_f32_dpp v40, v40, v40 quad_perm:[2,3,0,1] row_mask:0xf bank_mask:0xf
	s_nop 1
	v_add_f32_dpp v40, v40, v40 row_half_mirror row_mask:0xf bank_mask:0xf
	v_mul_f32_e32 v42, v40, v156
	v_fma_f32 v43, |v42|, s16, 1.0
	v_rcp_f32_e32 v43, v43
	v_cmp_gt_f32_e64 s[4:5], 0, v42
	v_mul_f32_e32 v45, v42, v42
	v_fmamk_f32 v44, v43, 0x3f07dc22, v142
	v_fmaak_f32 v44, v43, v44, 0x3f35f0e3
	v_fmaak_f32 v44, v43, v44, 0xbe11a98e
	v_fmaak_f32 v44, v43, v44, 0x3e027906
	v_mul_f32_e32 v45, 0xbf38aa3b, v45
	v_exp_f32_e32 v45, v45
	v_mul_f32_e32 v43, v43, v44
	v_mul_f32_e32 v43, v45, v43
	v_mul_f32_e32 v44, v42, v43
	v_fma_f32 v42, -v42, v43, v42
	v_cndmask_b32_e64 v42, v42, v44, s[4:5]
	v_mul_f32_e32 v158, v42, v157
	ds_bpermute_b32 v118, v138, v158
	ds_bpermute_b32 v120, v139, v158
	ds_bpermute_b32 v122, v140, v158
	ds_bpermute_b32 v124, v141, v158
	s_waitcnt vmcnt(11)
	v_cvt_scalef32_pk_f32_fp4 v[224:225], v208, 1.0
	v_cvt_scalef32_pk_f32_fp4 v[226:227], v208, 1.0 op_sel:[1,0,0]
	s_waitcnt lgkmcnt(0)
	v_cvt_scalef32_pk_f32_fp4 v[228:229], v208, 1.0 op_sel:[0,1,0]
	v_pk_fma_f32 v[112:113], v[224:225], v[118:119], v[112:113] op_sel_hi:[1,0,1]
	v_cvt_scalef32_pk_f32_fp4 v[230:231], v208, 1.0 op_sel:[1,1,0]
	v_pk_fma_f32 v[108:109], v[226:227], v[118:119], v[108:109] op_sel_hi:[1,0,1]
	v_cvt_scalef32_pk_f32_fp4 v[224:225], v209, 1.0
	v_pk_fma_f32 v[104:105], v[228:229], v[118:119], v[104:105] op_sel_hi:[1,0,1]
	v_cvt_scalef32_pk_f32_fp4 v[226:227], v209, 1.0 op_sel:[1,0,0]
	v_pk_fma_f32 v[98:99], v[230:231], v[118:119], v[98:99] op_sel_hi:[1,0,1]
	v_cvt_scalef32_pk_f32_fp4 v[228:229], v209, 1.0 op_sel:[0,1,0]
	v_pk_fma_f32 v[54:55], v[224:225], v[118:119], v[54:55] op_sel_hi:[1,0,1]
	v_cvt_scalef32_pk_f32_fp4 v[230:231], v209, 1.0 op_sel:[1,1,0]
	v_pk_fma_f32 v[58:59], v[226:227], v[118:119], v[58:59] op_sel_hi:[1,0,1]
	v_cvt_scalef32_pk_f32_fp4 v[224:225], v210, 1.0
	v_pk_fma_f32 v[52:53], v[228:229], v[118:119], v[52:53] op_sel_hi:[1,0,1]
	v_cvt_scalef32_pk_f32_fp4 v[226:227], v210, 1.0 op_sel:[1,0,0]
	v_pk_fma_f32 v[48:49], v[230:231], v[118:119], v[48:49] op_sel_hi:[1,0,1]
	v_cvt_scalef32_pk_f32_fp4 v[228:229], v210, 1.0 op_sel:[0,1,0]
	v_pk_fma_f32 v[106:107], v[224:225], v[118:119], v[106:107] op_sel_hi:[1,0,1]
	v_cvt_scalef32_pk_f32_fp4 v[230:231], v210, 1.0 op_sel:[1,1,0]
	v_pk_fma_f32 v[102:103], v[226:227], v[118:119], v[102:103] op_sel_hi:[1,0,1]
	v_cvt_scalef32_pk_f32_fp4 v[224:225], v211, 1.0
	v_pk_fma_f32 v[96:97], v[228:229], v[118:119], v[96:97] op_sel_hi:[1,0,1]
	v_cvt_scalef32_pk_f32_fp4 v[226:227], v211, 1.0 op_sel:[1,0,0]
	v_pk_fma_f32 v[56:57], v[230:231], v[118:119], v[56:57] op_sel_hi:[1,0,1]
	v_cvt_scalef32_pk_f32_fp4 v[228:229], v211, 1.0 op_sel:[0,1,0]
	v_pk_fma_f32 v[50:51], v[224:225], v[118:119], v[50:51] op_sel_hi:[1,0,1]
	v_cvt_scalef32_pk_f32_fp4 v[230:231], v211, 1.0 op_sel:[1,1,0]
	v_pk_fma_f32 v[114:115], v[226:227], v[118:119], v[114:115] op_sel_hi:[1,0,1]
	v_pk_fma_f32 v[110:111], v[228:229], v[118:119], v[110:111] op_sel_hi:[1,0,1]
	v_pk_fma_f32 v[100:101], v[230:231], v[118:119], v[100:101] op_sel_hi:[1,0,1]
	s_waitcnt vmcnt(10)
	v_cvt_scalef32_pk_f32_fp4 v[224:225], v212, 1.0
	v_cvt_scalef32_pk_f32_fp4 v[226:227], v212, 1.0 op_sel:[1,0,0]
	v_cvt_scalef32_pk_f32_fp4 v[228:229], v212, 1.0 op_sel:[0,1,0]
	v_pk_fma_f32 v[112:113], v[224:225], v[120:121], v[112:113] op_sel_hi:[1,0,1]
	v_cvt_scalef32_pk_f32_fp4 v[230:231], v212, 1.0 op_sel:[1,1,0]
	v_pk_fma_f32 v[108:109], v[226:227], v[120:121], v[108:109] op_sel_hi:[1,0,1]
	v_cvt_scalef32_pk_f32_fp4 v[224:225], v213, 1.0
	v_pk_fma_f32 v[104:105], v[228:229], v[120:121], v[104:105] op_sel_hi:[1,0,1]
	v_cvt_scalef32_pk_f32_fp4 v[226:227], v213, 1.0 op_sel:[1,0,0]
	v_pk_fma_f32 v[98:99], v[230:231], v[120:121], v[98:99] op_sel_hi:[1,0,1]
	v_cvt_scalef32_pk_f32_fp4 v[228:229], v213, 1.0 op_sel:[0,1,0]
	v_pk_fma_f32 v[54:55], v[224:225], v[120:121], v[54:55] op_sel_hi:[1,0,1]
	v_cvt_scalef32_pk_f32_fp4 v[230:231], v213, 1.0 op_sel:[1,1,0]
	v_pk_fma_f32 v[58:59], v[226:227], v[120:121], v[58:59] op_sel_hi:[1,0,1]
	v_cvt_scalef32_pk_f32_fp4 v[224:225], v214, 1.0
	v_pk_fma_f32 v[52:53], v[228:229], v[120:121], v[52:53] op_sel_hi:[1,0,1]
	v_cvt_scalef32_pk_f32_fp4 v[226:227], v214, 1.0 op_sel:[1,0,0]
	v_pk_fma_f32 v[48:49], v[230:231], v[120:121], v[48:49] op_sel_hi:[1,0,1]
	v_cvt_scalef32_pk_f32_fp4 v[228:229], v214, 1.0 op_sel:[0,1,0]
	v_pk_fma_f32 v[106:107], v[224:225], v[120:121], v[106:107] op_sel_hi:[1,0,1]
	v_cvt_scalef32_pk_f32_fp4 v[230:231], v214, 1.0 op_sel:[1,1,0]
	v_pk_fma_f32 v[102:103], v[226:227], v[120:121], v[102:103] op_sel_hi:[1,0,1]
	v_cvt_scalef32_pk_f32_fp4 v[224:225], v215, 1.0
	v_pk_fma_f32 v[96:97], v[228:229], v[120:121], v[96:97] op_sel_hi:[1,0,1]
	v_cvt_scalef32_pk_f32_fp4 v[226:227], v215, 1.0 op_sel:[1,0,0]
	v_pk_fma_f32 v[56:57], v[230:231], v[120:121], v[56:57] op_sel_hi:[1,0,1]
	v_cvt_scalef32_pk_f32_fp4 v[228:229], v215, 1.0 op_sel:[0,1,0]
	v_pk_fma_f32 v[50:51], v[224:225], v[120:121], v[50:51] op_sel_hi:[1,0,1]
	v_cvt_scalef32_pk_f32_fp4 v[230:231], v215, 1.0 op_sel:[1,1,0]
	v_pk_fma_f32 v[114:115], v[226:227], v[120:121], v[114:115] op_sel_hi:[1,0,1]
	v_pk_fma_f32 v[110:111], v[228:229], v[120:121], v[110:111] op_sel_hi:[1,0,1]
	v_pk_fma_f32 v[100:101], v[230:231], v[120:121], v[100:101] op_sel_hi:[1,0,1]
	s_waitcnt vmcnt(9)
	v_cvt_scalef32_pk_f32_fp4 v[224:225], v216, 1.0
	v_cvt_scalef32_pk_f32_fp4 v[226:227], v216, 1.0 op_sel:[1,0,0]
	v_cvt_scalef32_pk_f32_fp4 v[228:229], v216, 1.0 op_sel:[0,1,0]
	v_pk_fma_f32 v[112:113], v[224:225], v[122:123], v[112:113] op_sel_hi:[1,0,1]
	v_cvt_scalef32_pk_f32_fp4 v[230:231], v216, 1.0 op_sel:[1,1,0]
	v_pk_fma_f32 v[108:109], v[226:227], v[122:123], v[108:109] op_sel_hi:[1,0,1]
	v_cvt_scalef32_pk_f32_fp4 v[224:225], v217, 1.0
	v_pk_fma_f32 v[104:105], v[228:229], v[122:123], v[104:105] op_sel_hi:[1,0,1]
	v_cvt_scalef32_pk_f32_fp4 v[226:227], v217, 1.0 op_sel:[1,0,0]
	v_pk_fma_f32 v[98:99], v[230:231], v[122:123], v[98:99] op_sel_hi:[1,0,1]
	v_cvt_scalef32_pk_f32_fp4 v[228:229], v217, 1.0 op_sel:[0,1,0]
	v_pk_fma_f32 v[54:55], v[224:225], v[122:123], v[54:55] op_sel_hi:[1,0,1]
	v_cvt_scalef32_pk_f32_fp4 v[230:231], v217, 1.0 op_sel:[1,1,0]
	v_pk_fma_f32 v[58:59], v[226:227], v[122:123], v[58:59] op_sel_hi:[1,0,1]
	v_cvt_scalef32_pk_f32_fp4 v[224:225], v218, 1.0
	v_pk_fma_f32 v[52:53], v[228:229], v[122:123], v[52:53] op_sel_hi:[1,0,1]
	v_cvt_scalef32_pk_f32_fp4 v[226:227], v218, 1.0 op_sel:[1,0,0]
	v_pk_fma_f32 v[48:49], v[230:231], v[122:123], v[48:49] op_sel_hi:[1,0,1]
	v_cvt_scalef32_pk_f32_fp4 v[228:229], v218, 1.0 op_sel:[0,1,0]
	v_pk_fma_f32 v[106:107], v[224:225], v[122:123], v[106:107] op_sel_hi:[1,0,1]
	v_cvt_scalef32_pk_f32_fp4 v[230:231], v218, 1.0 op_sel:[1,1,0]
	v_pk_fma_f32 v[102:103], v[226:227], v[122:123], v[102:103] op_sel_hi:[1,0,1]
	v_cvt_scalef32_pk_f32_fp4 v[224:225], v219, 1.0
	v_pk_fma_f32 v[96:97], v[228:229], v[122:123], v[96:97] op_sel_hi:[1,0,1]
	v_cvt_scalef32_pk_f32_fp4 v[226:227], v219, 1.0 op_sel:[1,0,0]
	v_pk_fma_f32 v[56:57], v[230:231], v[122:123], v[56:57] op_sel_hi:[1,0,1]
	v_cvt_scalef32_pk_f32_fp4 v[228:229], v219, 1.0 op_sel:[0,1,0]
	v_pk_fma_f32 v[50:51], v[224:225], v[122:123], v[50:51] op_sel_hi:[1,0,1]
	v_cvt_scalef32_pk_f32_fp4 v[230:231], v219, 1.0 op_sel:[1,1,0]
	v_pk_fma_f32 v[114:115], v[226:227], v[122:123], v[114:115] op_sel_hi:[1,0,1]
	v_pk_fma_f32 v[110:111], v[228:229], v[122:123], v[110:111] op_sel_hi:[1,0,1]
	v_pk_fma_f32 v[100:101], v[230:231], v[122:123], v[100:101] op_sel_hi:[1,0,1]
	s_waitcnt vmcnt(8)
	v_cvt_scalef32_pk_f32_fp4 v[224:225], v220, 1.0
	v_cvt_scalef32_pk_f32_fp4 v[226:227], v220, 1.0 op_sel:[1,0,0]
	v_cvt_scalef32_pk_f32_fp4 v[228:229], v220, 1.0 op_sel:[0,1,0]
	v_pk_fma_f32 v[112:113], v[224:225], v[124:125], v[112:113] op_sel_hi:[1,0,1]
	v_cvt_scalef32_pk_f32_fp4 v[230:231], v220, 1.0 op_sel:[1,1,0]
	v_pk_fma_f32 v[108:109], v[226:227], v[124:125], v[108:109] op_sel_hi:[1,0,1]
	v_cvt_scalef32_pk_f32_fp4 v[224:225], v221, 1.0
	v_pk_fma_f32 v[104:105], v[228:229], v[124:125], v[104:105] op_sel_hi:[1,0,1]
	v_cvt_scalef32_pk_f32_fp4 v[226:227], v221, 1.0 op_sel:[1,0,0]
	v_pk_fma_f32 v[98:99], v[230:231], v[124:125], v[98:99] op_sel_hi:[1,0,1]
	v_cvt_scalef32_pk_f32_fp4 v[228:229], v221, 1.0 op_sel:[0,1,0]
	v_pk_fma_f32 v[54:55], v[224:225], v[124:125], v[54:55] op_sel_hi:[1,0,1]
	v_cvt_scalef32_pk_f32_fp4 v[230:231], v221, 1.0 op_sel:[1,1,0]
	v_pk_fma_f32 v[58:59], v[226:227], v[124:125], v[58:59] op_sel_hi:[1,0,1]
	v_cvt_scalef32_pk_f32_fp4 v[224:225], v222, 1.0
	v_pk_fma_f32 v[52:53], v[228:229], v[124:125], v[52:53] op_sel_hi:[1,0,1]
	v_cvt_scalef32_pk_f32_fp4 v[226:227], v222, 1.0 op_sel:[1,0,0]
	v_pk_fma_f32 v[48:49], v[230:231], v[124:125], v[48:49] op_sel_hi:[1,0,1]
	v_cvt_scalef32_pk_f32_fp4 v[228:229], v222, 1.0 op_sel:[0,1,0]
	v_pk_fma_f32 v[106:107], v[224:225], v[124:125], v[106:107] op_sel_hi:[1,0,1]
	v_cvt_scalef32_pk_f32_fp4 v[230:231], v222, 1.0 op_sel:[1,1,0]
	v_pk_fma_f32 v[102:103], v[226:227], v[124:125], v[102:103] op_sel_hi:[1,0,1]
	v_cvt_scalef32_pk_f32_fp4 v[224:225], v223, 1.0
	v_pk_fma_f32 v[96:97], v[228:229], v[124:125], v[96:97] op_sel_hi:[1,0,1]
	v_cvt_scalef32_pk_f32_fp4 v[226:227], v223, 1.0 op_sel:[1,0,0]
	v_pk_fma_f32 v[56:57], v[230:231], v[124:125], v[56:57] op_sel_hi:[1,0,1]
	v_cvt_scalef32_pk_f32_fp4 v[228:229], v223, 1.0 op_sel:[0,1,0]
	v_pk_fma_f32 v[50:51], v[224:225], v[124:125], v[50:51] op_sel_hi:[1,0,1]
	v_cvt_scalef32_pk_f32_fp4 v[230:231], v223, 1.0 op_sel:[1,1,0]
	v_pk_fma_f32 v[114:115], v[226:227], v[124:125], v[114:115] op_sel_hi:[1,0,1]
	v_pk_fma_f32 v[110:111], v[228:229], v[124:125], v[110:111] op_sel_hi:[1,0,1]
	v_pk_fma_f32 v[100:101], v[230:231], v[124:125], v[100:101] op_sel_hi:[1,0,1]
	s_add_u32 s19, s19, 2
	s_cmp_lt_u32 s19, 14
	s_cbranch_scc1 .Lxg_loop_p12
	s_waitcnt lgkmcnt(0)
	v_lshl_add_u32 v250, v240, 9, v241
	v_lshl_add_u32 v251, v242, 9, v241
	v_lshl_add_u32 v252, v246, 9, v241
	v_lshl_add_u32 v253, v248, 9, v241
	global_load_dwordx4 v[192:195], v250, s[98:99]
	global_load_dwordx4 v[196:199], v251, s[98:99]
	global_load_dwordx4 v[200:203], v252, s[98:99]
	global_load_dwordx4 v[204:207], v253, s[98:99]
	global_load_dwordx4 v[208:211], v250, s[100:101]
	global_load_dwordx4 v[212:215], v251, s[100:101]
	global_load_dwordx4 v[216:219], v252, s[100:101]
	global_load_dwordx4 v[220:223], v253, s[100:101]
	s_movk_i32 s20, 0xc0
	v_lshl_add_u32 v130, v137, 2, s20
	ds_bpermute_b32 v156, v130, v147
	ds_bpermute_b32 v157, v130, v149
	s_waitcnt vmcnt(14)
	v_cvt_scalef32_pk_f32_fp4 v[224:225], v160, 1.0
	v_cvt_scalef32_pk_f32_fp4 v[226:227], v164, 1.0
	v_cvt_scalef32_pk_f32_fp4 v[228:229], v160, 1.0 op_sel:[1,0,0]
	v_cvt_scalef32_pk_f32_fp4 v[230:231], v164, 1.0 op_sel:[1,0,0]
	v_pk_fma_f32 v[232:233], v[24:25], v[224:225], 0 op_sel_hi:[1,1,0]
	v_pk_fma_f32 v[234:235], v[24:25], v[226:227], 0 op_sel_hi:[1,1,0]
	v_cvt_scalef32_pk_f32_fp4 v[224:225], v160, 1.0 op_sel:[0,1,0]
	v_cvt_scalef32_pk_f32_fp4 v[226:227], v164, 1.0 op_sel:[0,1,0]
	v_pk_fma_f32 v[232:233], v[26:27], v[228:229], v[232:233]
	v_pk_fma_f32 v[234:235], v[26:27], v[230:231], v[234:235]
	v_cvt_scalef32_pk_f32_fp4 v[228:229], v160, 1.0 op_sel:[1,1,0]
	v_cvt_scalef32_pk_f32_fp4 v[230:231], v164, 1.0 op_sel:[1,1,0]
	v_pk_fma_f32 v[232:233], v[12:13], v[224:225], v[232:233]
	v_pk_fma_f32 v[234:235], v[12:13], v[226:227], v[234:235]
	v_cvt_scalef32_pk_f32_fp4 v[224:225], v161, 1.0
	v_cvt_scalef32_pk_f32_fp4 v[226:227], v165, 1.0
	v_pk_fma_f32 v[232:233], v[14:15], v[228:229], v[232:233]
	v_pk_fma_f32 v[234:235], v[14:15], v[230:231], v[234:235]
	v_cvt_scalef32_pk_f32_fp4 v[228:229], v161, 1.0 op_sel:[1,0,0]
	v_cvt_scalef32_pk_f32_fp4 v[230:231], v165, 1.0 op_sel:[1,0,0]
	v_pk_fma_f32 v[232:233], v[4:5], v[224:225], v[232:233]
	v_pk_fma_f32 v[234:235], v[4:5], v[226:227], v[234:235]
	v_cvt_scalef32_pk_f32_fp4 v[224:225], v161, 1.0 op_sel:[0,1,0]
	v_cvt_scalef32_pk_f32_fp4 v[226:227], v165, 1.0 op_sel:[0,1,0]
	v_pk_fma_f32 v[232:233], v[6:7], v[228:229], v[232:233]
	v_pk_fma_f32 v[234:235], v[6:7], v[230:231], v[234:235]
	v_cvt_scalef32_pk_f32_fp4 v[228:229], v161, 1.0 op_sel:[1,1,0]
	v_cvt_scalef32_pk_f32_fp4 v[230:231], v165, 1.0 op_sel:[1,1,0]
	v_pk_fma_f32 v[232:233], v[0:1], v[224:225], v[232:233]
	v_pk_fma_f32 v[234:235], v[0:1], v[226:227], v[234:235]
	v_cvt_scalef32_pk_f32_fp4 v[224:225], v162, 1.0
	v_cvt_scalef32_pk_f32_fp4 v[226:227], v166, 1.0
	v_pk_fma_f32 v[232:233], v[2:3], v[228:229], v[232:233]
	v_pk_fma_f32 v[234:235], v[2:3], v[230:231], v[234:235]
	v_cvt_scalef32_pk_f32_fp4 v[228:229], v162, 1.0 op_sel:[1,0,0]
	v_cvt_scalef32_pk_f32_fp4 v[230:231], v166, 1.0 op_sel:[1,0,0]
	v_pk_fma_f32 v[232:233], v[28:29], v[224:225], v[232:233]
	v_pk_fma_f32 v[234:235], v[28:29], v[226:227], v[234:235]
	v_cvt_scalef32_pk_f32_fp4 v[224:225], v162, 1.0 op_sel:[0,1,0]
	v_cvt_scalef32_pk_f32_fp4 v[226:227], v166, 1.0 op_sel:[0,1,0]
	v_pk_fma_f32 v[232:233], v[30:31], v[228:229], v[232:233]
	v_pk_fma_f32 v[234:235], v[30:31], v[230:231], v[234:235]
	v_cvt_scalef32_pk_f32_fp4 v[228:229], v162, 1.0 op_sel:[1,1,0]
	v_cvt_scalef32_pk_f32_fp4 v[230:231], v166, 1.0 op_sel:[1,1,0]
	v_pk_fma_f32 v[232:233], v[16:17], v[224:225], v[232:233]
	v_pk_fma_f32 v[234:235], v[16:17], v[226:227], v[234:235]
	v_cvt_scalef32_pk_f32_fp4 v[224:225], v163, 1.0
	v_cvt_scalef32_pk_f32_fp4 v[226:227], v167, 1.0
	v_pk_fma_f32 v[232:233], v[18:19], v[228:229], v[232:233]
	v_pk_fma_f32 v[234:235], v[18:19], v[230:231], v[234:235]
	v_cvt_scalef32_pk_f32_fp4 v[228:229], v163, 1.0 op_sel:[1,0,0]
	v_cvt_scalef32_pk_f32_fp4 v[230:231], v167, 1.0 op_sel:[1,0,0]
	v_pk_fma_f32 v[232:233], v[8:9], v[224:225], v[232:233]
	v_pk_fma_f32 v[234:235], v[8:9], v[226:227], v[234:235]
	v_cvt_scalef32_pk_f32_fp4 v[224:225], v163, 1.0 op_sel:[0,1,0]
	v_cvt_scalef32_pk_f32_fp4 v[226:227], v167, 1.0 op_sel:[0,1,0]
	v_pk_fma_f32 v[232:233], v[10:11], v[228:229], v[232:233]
	v_pk_fma_f32 v[234:235], v[10:11], v[230:231], v[234:235]
	v_cvt_scalef32_pk_f32_fp4 v[228:229], v163, 1.0 op_sel:[1,1,0]
	v_cvt_scalef32_pk_f32_fp4 v[230:231], v167, 1.0 op_sel:[1,1,0]
	v_pk_fma_f32 v[232:233], v[20:21], v[224:225], v[232:233]
	v_pk_fma_f32 v[234:235], v[20:21], v[226:227], v[234:235]
	v_pk_fma_f32 v[232:233], v[22:23], v[228:229], v[232:233]
	v_pk_fma_f32 v[234:235], v[22:23], v[230:231], v[234:235]
	v_add_f32_e32 v32, v232, v233
	v_add_f32_e32 v33, v234, v235
	s_waitcnt vmcnt(12)
	v_cvt_scalef32_pk_f32_fp4 v[224:225], v168, 1.0
	v_cvt_scalef32_pk_f32_fp4 v[226:227], v172, 1.0
	v_cvt_scalef32_pk_f32_fp4 v[228:229], v168, 1.0 op_sel:[1,0,0]
	v_cvt_scalef32_pk_f32_fp4 v[230:231], v172, 1.0 op_sel:[1,0,0]
	v_pk_fma_f32 v[236:237], v[24:25], v[224:225], 0 op_sel_hi:[1,1,0]
	v_pk_fma_f32 v[238:239], v[24:25], v[226:227], 0 op_sel_hi:[1,1,0]
	v_cvt_scalef32_pk_f32_fp4 v[224:225], v168, 1.0 op_sel:[0,1,0]
	v_cvt_scalef32_pk_f32_fp4 v[226:227], v172, 1.0 op_sel:[0,1,0]
	v_pk_fma_f32 v[236:237], v[26:27], v[228:229], v[236:237]
	v_pk_fma_f32 v[238:239], v[26:27], v[230:231], v[238:239]
	v_cvt_scalef32_pk_f32_fp4 v[228:229], v168, 1.0 op_sel:[1,1,0]
	v_cvt_scalef32_pk_f32_fp4 v[230:231], v172, 1.0 op_sel:[1,1,0]
	v_pk_fma_f32 v[236:237], v[12:13], v[224:225], v[236:237]
	v_pk_fma_f32 v[238:239], v[12:13], v[226:227], v[238:239]
	v_cvt_scalef32_pk_f32_fp4 v[224:225], v169, 1.0
	v_cvt_scalef32_pk_f32_fp4 v[226:227], v173, 1.0
	v_pk_fma_f32 v[236:237], v[14:15], v[228:229], v[236:237]
	v_pk_fma_f32 v[238:239], v[14:15], v[230:231], v[238:239]
	v_cvt_scalef32_pk_f32_fp4 v[228:229], v169, 1.0 op_sel:[1,0,0]
	v_cvt_scalef32_pk_f32_fp4 v[230:231], v173, 1.0 op_sel:[1,0,0]
	v_pk_fma_f32 v[236:237], v[4:5], v[224:225], v[236:237]
	v_pk_fma_f32 v[238:239], v[4:5], v[226:227], v[238:239]
	v_cvt_scalef32_pk_f32_fp4 v[224:225], v169, 1.0 op_sel:[0,1,0]
	v_cvt_scalef32_pk_f32_fp4 v[226:227], v173, 1.0 op_sel:[0,1,0]
	v_pk_fma_f32 v[236:237], v[6:7], v[228:229], v[236:237]
	v_pk_fma_f32 v[238:239], v[6:7], v[230:231], v[238:239]
	v_cvt_scalef32_pk_f32_fp4 v[228:229], v169, 1.0 op_sel:[1,1,0]
	v_cvt_scalef32_pk_f32_fp4 v[230:231], v173, 1.0 op_sel:[1,1,0]
	v_pk_fma_f32 v[236:237], v[0:1], v[224:225], v[236:237]
	v_pk_fma_f32 v[238:239], v[0:1], v[226:227], v[238:239]
	v_cvt_scalef32_pk_f32_fp4 v[224:225], v170, 1.0
	v_cvt_scalef32_pk_f32_fp4 v[226:227], v174, 1.0
	v_pk_fma_f32 v[236:237], v[2:3], v[228:229], v[236:237]
	v_pk_fma_f32 v[238:239], v[2:3], v[230:231], v[238:239]
	v_cvt_scalef32_pk_f32_fp4 v[228:229], v170, 1.0 op_sel:[1,0,0]
	v_cvt_scalef32_pk_f32_fp4 v[230:231], v174, 1.0 op_sel:[1,0,0]
	v_pk_fma_f32 v[236:237], v[28:29], v[224:225], v[236:237]
	v_pk_fma_f32 v[238:239], v[28:29], v[226:227], v[238:239]
	v_cvt_scalef32_pk_f32_fp4 v[224:225], v170, 1.0 op_sel:[0,1,0]
	v_cvt_scalef32_pk_f32_fp4 v[226:227], v174, 1.0 op_sel:[0,1,0]
	v_pk_fma_f32 v[236:237], v[30:31], v[228:229], v[236:237]
	v_pk_fma_f32 v[238:239], v[30:31], v[230:231], v[238:239]
	v_cvt_scalef32_pk_f32_fp4 v[228:229], v170, 1.0 op_sel:[1,1,0]
	v_cvt_scalef32_pk_f32_fp4 v[230:231], v174, 1.0 op_sel:[1,1,0]
	v_pk_fma_f32 v[236:237], v[16:17], v[224:225], v[236:237]
	v_pk_fma_f32 v[238:239], v[16:17], v[226:227], v[238:239]
	v_cvt_scalef32_pk_f32_fp4 v[224:225], v171, 1.0
	v_cvt_scalef32_pk_f32_fp4 v[226:227], v175, 1.0
	v_pk_fma_f32 v[236:237], v[18:19], v[228:229], v[236:237]
	v_pk_fma_f32 v[238:239], v[18:19], v[230:231], v[238:239]
	v_cvt_scalef32_pk_f32_fp4 v[228:229], v171, 1.0 op_sel:[1,0,0]
	v_cvt_scalef32_pk_f32_fp4 v[230:231], v175, 1.0 op_sel:[1,0,0]
	v_pk_fma_f32 v[236:237], v[8:9], v[224:225], v[236:237]
	v_pk_fma_f32 v[238:239], v[8:9], v[226:227], v[238:239]
	v_cvt_scalef32_pk_f32_fp4 v[224:225], v171, 1.0 op_sel:[0,1,0]
	v_cvt_scalef32_pk_f32_fp4 v[226:227], v175, 1.0 op_sel:[0,1,0]
	v_pk_fma_f32 v[236:237], v[10:11], v[228:229], v[236:237]
	v_pk_fma_f32 v[238:239], v[10:11], v[230:231], v[238:239]
	v_cvt_scalef32_pk_f32_fp4 v[228:229], v171, 1.0 op_sel:[1,1,0]
	v_cvt_scalef32_pk_f32_fp4 v[230:231], v175, 1.0 op_sel:[1,1,0]
	v_pk_fma_f32 v[236:237], v[20:21], v[224:225], v[236:237]
	v_pk_fma_f32 v[238:239], v[20:21], v[226:227], v[238:239]
	v_pk_fma_f32 v[236:237], v[22:23], v[228:229], v[236:237]
	v_pk_fma_f32 v[238:239], v[22:23], v[230:231], v[238:239]
	v_add_f32_e32 v34, v236, v237
	v_add_f32_e32 v35, v238, v239
	s_nop 1
	v_permlane16_swap_b32_e32 v32, v34
	v_permlane16_swap_b32_e32 v33, v35
	v_add_f32_e32 v36, v32, v34
	v_add_f32_e32 v38, v33, v35
	s_waitcnt lgkmcnt(0)
	v_cndmask_b32_e64 v40, v38, v36, s[0:1]
	v_cndmask_b32_e64 v41, v36, v38, s[0:1]
	s_nop 1
	v_add_f32_dpp v40, v41, v40 row_ror:8 row_mask:0xf bank_mask:0xf
	s_nop 1
	v_add_f32_dpp v40, v40, v40 quad_perm:[1,0,3,2] row_mask:0xf bank_mask:0xf
	s_nop 1
	v_add_f32_dpp v40, v40, v40 quad_perm:[2,3,0,1] row_mask:0xf bank_mask:0xf
	s_nop 1
	v_add_f32_dpp v40, v40, v40 row_half_mirror row_mask:0xf bank_mask:0xf
	v_mul_f32_e32 v42, v40, v156
	v_fma_f32 v43, |v42|, s16, 1.0
	v_rcp_f32_e32 v43, v43
	v_cmp_gt_f32_e64 s[4:5], 0, v42
	v_mul_f32_e32 v45, v42, v42
	v_fmamk_f32 v44, v43, 0x3f07dc22, v142
	v_fmaak_f32 v44, v43, v44, 0x3f35f0e3
	v_fmaak_f32 v44, v43, v44, 0xbe11a98e
	v_fmaak_f32 v44, v43, v44, 0x3e027906
	v_mul_f32_e32 v45, 0xbf38aa3b, v45
	v_exp_f32_e32 v45, v45
	v_mul_f32_e32 v43, v43, v44
	v_mul_f32_e32 v43, v45, v43
	v_mul_f32_e32 v44, v42, v43
	v_fma_f32 v42, -v42, v43, v42
	v_cndmask_b32_e64 v42, v42, v44, s[4:5]
	v_mul_f32_e32 v158, v42, v157
	ds_bpermute_b32 v118, v138, v158
	ds_bpermute_b32 v120, v139, v158
	ds_bpermute_b32 v122, v140, v158
	ds_bpermute_b32 v124, v141, v158
	s_waitcnt vmcnt(11)
	v_cvt_scalef32_pk_f32_fp4 v[224:225], v176, 1.0
	v_cvt_scalef32_pk_f32_fp4 v[226:227], v176, 1.0 op_sel:[1,0,0]
	s_waitcnt lgkmcnt(0)
	v_cvt_scalef32_pk_f32_fp4 v[228:229], v176, 1.0 op_sel:[0,1,0]
	v_pk_fma_f32 v[112:113], v[224:225], v[118:119], v[112:113] op_sel_hi:[1,0,1]
	v_cvt_scalef32_pk_f32_fp4 v[230:231], v176, 1.0 op_sel:[1,1,0]
	v_pk_fma_f32 v[108:109], v[226:227], v[118:119], v[108:109] op_sel_hi:[1,0,1]
	v_cvt_scalef32_pk_f32_fp4 v[224:225], v177, 1.0
	v_pk_fma_f32 v[104:105], v[228:229], v[118:119], v[104:105] op_sel_hi:[1,0,1]
	v_cvt_scalef32_pk_f32_fp4 v[226:227], v177, 1.0 op_sel:[1,0,0]
	v_pk_fma_f32 v[98:99], v[230:231], v[118:119], v[98:99] op_sel_hi:[1,0,1]
	v_cvt_scalef32_pk_f32_fp4 v[228:229], v177, 1.0 op_sel:[0,1,0]
	v_pk_fma_f32 v[54:55], v[224:225], v[118:119], v[54:55] op_sel_hi:[1,0,1]
	v_cvt_scalef32_pk_f32_fp4 v[230:231], v177, 1.0 op_sel:[1,1,0]
	v_pk_fma_f32 v[58:59], v[226:227], v[118:119], v[58:59] op_sel_hi:[1,0,1]
	v_cvt_scalef32_pk_f32_fp4 v[224:225], v178, 1.0
	v_pk_fma_f32 v[52:53], v[228:229], v[118:119], v[52:53] op_sel_hi:[1,0,1]
	v_cvt_scalef32_pk_f32_fp4 v[226:227], v178, 1.0 op_sel:[1,0,0]
	v_pk_fma_f32 v[48:49], v[230:231], v[118:119], v[48:49] op_sel_hi:[1,0,1]
	v_cvt_scalef32_pk_f32_fp4 v[228:229], v178, 1.0 op_sel:[0,1,0]
	v_pk_fma_f32 v[106:107], v[224:225], v[118:119], v[106:107] op_sel_hi:[1,0,1]
	v_cvt_scalef32_pk_f32_fp4 v[230:231], v178, 1.0 op_sel:[1,1,0]
	v_pk_fma_f32 v[102:103], v[226:227], v[118:119], v[102:103] op_sel_hi:[1,0,1]
	v_cvt_scalef32_pk_f32_fp4 v[224:225], v179, 1.0
	v_pk_fma_f32 v[96:97], v[228:229], v[118:119], v[96:97] op_sel_hi:[1,0,1]
	v_cvt_scalef32_pk_f32_fp4 v[226:227], v179, 1.0 op_sel:[1,0,0]
	v_pk_fma_f32 v[56:57], v[230:231], v[118:119], v[56:57] op_sel_hi:[1,0,1]
	v_cvt_scalef32_pk_f32_fp4 v[228:229], v179, 1.0 op_sel:[0,1,0]
	v_pk_fma_f32 v[50:51], v[224:225], v[118:119], v[50:51] op_sel_hi:[1,0,1]
	v_cvt_scalef32_pk_f32_fp4 v[230:231], v179, 1.0 op_sel:[1,1,0]
	v_pk_fma_f32 v[114:115], v[226:227], v[118:119], v[114:115] op_sel_hi:[1,0,1]
	v_pk_fma_f32 v[110:111], v[228:229], v[118:119], v[110:111] op_sel_hi:[1,0,1]
	v_pk_fma_f32 v[100:101], v[230:231], v[118:119], v[100:101] op_sel_hi:[1,0,1]
	s_waitcnt vmcnt(10)
	v_cvt_scalef32_pk_f32_fp4 v[224:225], v180, 1.0
	v_cvt_scalef32_pk_f32_fp4 v[226:227], v180, 1.0 op_sel:[1,0,0]
	v_cvt_scalef32_pk_f32_fp4 v[228:229], v180, 1.0 op_sel:[0,1,0]
	v_pk_fma_f32 v[112:113], v[224:225], v[120:121], v[112:113] op_sel_hi:[1,0,1]
	v_cvt_scalef32_pk_f32_fp4 v[230:231], v180, 1.0 op_sel:[1,1,0]
	v_pk_fma_f32 v[108:109], v[226:227], v[120:121], v[108:109] op_sel_hi:[1,0,1]
	v_cvt_scalef32_pk_f32_fp4 v[224:225], v181, 1.0
	v_pk_fma_f32 v[104:105], v[228:229], v[120:121], v[104:105] op_sel_hi:[1,0,1]
	v_cvt_scalef32_pk_f32_fp4 v[226:227], v181, 1.0 op_sel:[1,0,0]
	v_pk_fma_f32 v[98:99], v[230:231], v[120:121], v[98:99] op_sel_hi:[1,0,1]
	v_cvt_scalef32_pk_f32_fp4 v[228:229], v181, 1.0 op_sel:[0,1,0]
	v_pk_fma_f32 v[54:55], v[224:225], v[120:121], v[54:55] op_sel_hi:[1,0,1]
	v_cvt_scalef32_pk_f32_fp4 v[230:231], v181, 1.0 op_sel:[1,1,0]
	v_pk_fma_f32 v[58:59], v[226:227], v[120:121], v[58:59] op_sel_hi:[1,0,1]
	v_cvt_scalef32_pk_f32_fp4 v[224:225], v182, 1.0
	v_pk_fma_f32 v[52:53], v[228:229], v[120:121], v[52:53] op_sel_hi:[1,0,1]
	v_cvt_scalef32_pk_f32_fp4 v[226:227], v182, 1.0 op_sel:[1,0,0]
	v_pk_fma_f32 v[48:49], v[230:231], v[120:121], v[48:49] op_sel_hi:[1,0,1]
	v_cvt_scalef32_pk_f32_fp4 v[228:229], v182, 1.0 op_sel:[0,1,0]
	v_pk_fma_f32 v[106:107], v[224:225], v[120:121], v[106:107] op_sel_hi:[1,0,1]
	v_cvt_scalef32_pk_f32_fp4 v[230:231], v182, 1.0 op_sel:[1,1,0]
	v_pk_fma_f32 v[102:103], v[226:227], v[120:121], v[102:103] op_sel_hi:[1,0,1]
	v_cvt_scalef32_pk_f32_fp4 v[224:225], v183, 1.0
	v_pk_fma_f32 v[96:97], v[228:229], v[120:121], v[96:97] op_sel_hi:[1,0,1]
	v_cvt_scalef32_pk_f32_fp4 v[226:227], v183, 1.0 op_sel:[1,0,0]
	v_pk_fma_f32 v[56:57], v[230:231], v[120:121], v[56:57] op_sel_hi:[1,0,1]
	v_cvt_scalef32_pk_f32_fp4 v[228:229], v183, 1.0 op_sel:[0,1,0]
	v_pk_fma_f32 v[50:51], v[224:225], v[120:121], v[50:51] op_sel_hi:[1,0,1]
	v_cvt_scalef32_pk_f32_fp4 v[230:231], v183, 1.0 op_sel:[1,1,0]
	v_pk_fma_f32 v[114:115], v[226:227], v[120:121], v[114:115] op_sel_hi:[1,0,1]
	v_pk_fma_f32 v[110:111], v[228:229], v[120:121], v[110:111] op_sel_hi:[1,0,1]
	v_pk_fma_f32 v[100:101], v[230:231], v[120:121], v[100:101] op_sel_hi:[1,0,1]
	s_waitcnt vmcnt(9)
	v_cvt_scalef32_pk_f32_fp4 v[224:225], v184, 1.0
	v_cvt_scalef32_pk_f32_fp4 v[226:227], v184, 1.0 op_sel:[1,0,0]
	v_cvt_scalef32_pk_f32_fp4 v[228:229], v184, 1.0 op_sel:[0,1,0]
	v_pk_fma_f32 v[112:113], v[224:225], v[122:123], v[112:113] op_sel_hi:[1,0,1]
	v_cvt_scalef32_pk_f32_fp4 v[230:231], v184, 1.0 op_sel:[1,1,0]
	v_pk_fma_f32 v[108:109], v[226:227], v[122:123], v[108:109] op_sel_hi:[1,0,1]
	v_cvt_scalef32_pk_f32_fp4 v[224:225], v185, 1.0
	v_pk_fma_f32 v[104:105], v[228:229], v[122:123], v[104:105] op_sel_hi:[1,0,1]
	v_cvt_scalef32_pk_f32_fp4 v[226:227], v185, 1.0 op_sel:[1,0,0]
	v_pk_fma_f32 v[98:99], v[230:231], v[122:123], v[98:99] op_sel_hi:[1,0,1]
	v_cvt_scalef32_pk_f32_fp4 v[228:229], v185, 1.0 op_sel:[0,1,0]
	v_pk_fma_f32 v[54:55], v[224:225], v[122:123], v[54:55] op_sel_hi:[1,0,1]
	v_cvt_scalef32_pk_f32_fp4 v[230:231], v185, 1.0 op_sel:[1,1,0]
	v_pk_fma_f32 v[58:59], v[226:227], v[122:123], v[58:59] op_sel_hi:[1,0,1]
	v_cvt_scalef32_pk_f32_fp4 v[224:225], v186, 1.0
	v_pk_fma_f32 v[52:53], v[228:229], v[122:123], v[52:53] op_sel_hi:[1,0,1]
	v_cvt_scalef32_pk_f32_fp4 v[226:227], v186, 1.0 op_sel:[1,0,0]
	v_pk_fma_f32 v[48:49], v[230:231], v[122:123], v[48:49] op_sel_hi:[1,0,1]
	v_cvt_scalef32_pk_f32_fp4 v[228:229], v186, 1.0 op_sel:[0,1,0]
	v_pk_fma_f32 v[106:107], v[224:225], v[122:123], v[106:107] op_sel_hi:[1,0,1]
	v_cvt_scalef32_pk_f32_fp4 v[230:231], v186, 1.0 op_sel:[1,1,0]
	v_pk_fma_f32 v[102:103], v[226:227], v[122:123], v[102:103] op_sel_hi:[1,0,1]
	v_cvt_scalef32_pk_f32_fp4 v[224:225], v187, 1.0
	v_pk_fma_f32 v[96:97], v[228:229], v[122:123], v[96:97] op_sel_hi:[1,0,1]
	v_cvt_scalef32_pk_f32_fp4 v[226:227], v187, 1.0 op_sel:[1,0,0]
	v_pk_fma_f32 v[56:57], v[230:231], v[122:123], v[56:57] op_sel_hi:[1,0,1]
	v_cvt_scalef32_pk_f32_fp4 v[228:229], v187, 1.0 op_sel:[0,1,0]
	v_pk_fma_f32 v[50:51], v[224:225], v[122:123], v[50:51] op_sel_hi:[1,0,1]
	v_cvt_scalef32_pk_f32_fp4 v[230:231], v187, 1.0 op_sel:[1,1,0]
	v_pk_fma_f32 v[114:115], v[226:227], v[122:123], v[114:115] op_sel_hi:[1,0,1]
	v_pk_fma_f32 v[110:111], v[228:229], v[122:123], v[110:111] op_sel_hi:[1,0,1]
	v_pk_fma_f32 v[100:101], v[230:231], v[122:123], v[100:101] op_sel_hi:[1,0,1]
	s_waitcnt vmcnt(8)
	v_cvt_scalef32_pk_f32_fp4 v[224:225], v188, 1.0
	v_cvt_scalef32_pk_f32_fp4 v[226:227], v188, 1.0 op_sel:[1,0,0]
	v_cvt_scalef32_pk_f32_fp4 v[228:229], v188, 1.0 op_sel:[0,1,0]
	v_pk_fma_f32 v[112:113], v[224:225], v[124:125], v[112:113] op_sel_hi:[1,0,1]
	v_cvt_scalef32_pk_f32_fp4 v[230:231], v188, 1.0 op_sel:[1,1,0]
	v_pk_fma_f32 v[108:109], v[226:227], v[124:125], v[108:109] op_sel_hi:[1,0,1]
	v_cvt_scalef32_pk_f32_fp4 v[224:225], v189, 1.0
	v_pk_fma_f32 v[104:105], v[228:229], v[124:125], v[104:105] op_sel_hi:[1,0,1]
	v_cvt_scalef32_pk_f32_fp4 v[226:227], v189, 1.0 op_sel:[1,0,0]
	v_pk_fma_f32 v[98:99], v[230:231], v[124:125], v[98:99] op_sel_hi:[1,0,1]
	v_cvt_scalef32_pk_f32_fp4 v[228:229], v189, 1.0 op_sel:[0,1,0]
	v_pk_fma_f32 v[54:55], v[224:225], v[124:125], v[54:55] op_sel_hi:[1,0,1]
	v_cvt_scalef32_pk_f32_fp4 v[230:231], v189, 1.0 op_sel:[1,1,0]
	v_pk_fma_f32 v[58:59], v[226:227], v[124:125], v[58:59] op_sel_hi:[1,0,1]
	v_cvt_scalef32_pk_f32_fp4 v[224:225], v190, 1.0
	v_pk_fma_f32 v[52:53], v[228:229], v[124:125], v[52:53] op_sel_hi:[1,0,1]
	v_cvt_scalef32_pk_f32_fp4 v[226:227], v190, 1.0 op_sel:[1,0,0]
	v_pk_fma_f32 v[48:49], v[230:231], v[124:125], v[48:49] op_sel_hi:[1,0,1]
	v_cvt_scalef32_pk_f32_fp4 v[228:229], v190, 1.0 op_sel:[0,1,0]
	v_pk_fma_f32 v[106:107], v[224:225], v[124:125], v[106:107] op_sel_hi:[1,0,1]
	v_cvt_scalef32_pk_f32_fp4 v[230:231], v190, 1.0 op_sel:[1,1,0]
	v_pk_fma_f32 v[102:103], v[226:227], v[124:125], v[102:103] op_sel_hi:[1,0,1]
	v_cvt_scalef32_pk_f32_fp4 v[224:225], v191, 1.0
	v_pk_fma_f32 v[96:97], v[228:229], v[124:125], v[96:97] op_sel_hi:[1,0,1]
	v_cvt_scalef32_pk_f32_fp4 v[226:227], v191, 1.0 op_sel:[1,0,0]
	v_pk_fma_f32 v[56:57], v[230:231], v[124:125], v[56:57] op_sel_hi:[1,0,1]
	v_cvt_scalef32_pk_f32_fp4 v[228:229], v191, 1.0 op_sel:[0,1,0]
	v_pk_fma_f32 v[50:51], v[224:225], v[124:125], v[50:51] op_sel_hi:[1,0,1]
	v_cvt_scalef32_pk_f32_fp4 v[230:231], v191, 1.0 op_sel:[1,1,0]
	v_pk_fma_f32 v[114:115], v[226:227], v[124:125], v[114:115] op_sel_hi:[1,0,1]
	v_pk_fma_f32 v[110:111], v[228:229], v[124:125], v[110:111] op_sel_hi:[1,0,1]
	v_pk_fma_f32 v[100:101], v[230:231], v[124:125], v[100:101] op_sel_hi:[1,0,1]
	s_waitcnt lgkmcnt(0)
	s_movk_i32 s20, 0xe0
	v_lshl_add_u32 v130, v137, 2, s20
	ds_bpermute_b32 v156, v130, v147
	ds_bpermute_b32 v157, v130, v149
	s_waitcnt vmcnt(6)
	v_cvt_scalef32_pk_f32_fp4 v[224:225], v192, 1.0
	v_cvt_scalef32_pk_f32_fp4 v[226:227], v196, 1.0
	v_cvt_scalef32_pk_f32_fp4 v[228:229], v192, 1.0 op_sel:[1,0,0]
	v_cvt_scalef32_pk_f32_fp4 v[230:231], v196, 1.0 op_sel:[1,0,0]
	v_pk_fma_f32 v[232:233], v[24:25], v[224:225], 0 op_sel_hi:[1,1,0]
	v_pk_fma_f32 v[234:235], v[24:25], v[226:227], 0 op_sel_hi:[1,1,0]
	v_cvt_scalef32_pk_f32_fp4 v[224:225], v192, 1.0 op_sel:[0,1,0]
	v_cvt_scalef32_pk_f32_fp4 v[226:227], v196, 1.0 op_sel:[0,1,0]
	v_pk_fma_f32 v[232:233], v[26:27], v[228:229], v[232:233]
	v_pk_fma_f32 v[234:235], v[26:27], v[230:231], v[234:235]
	v_cvt_scalef32_pk_f32_fp4 v[228:229], v192, 1.0 op_sel:[1,1,0]
	v_cvt_scalef32_pk_f32_fp4 v[230:231], v196, 1.0 op_sel:[1,1,0]
	v_pk_fma_f32 v[232:233], v[12:13], v[224:225], v[232:233]
	v_pk_fma_f32 v[234:235], v[12:13], v[226:227], v[234:235]
	v_cvt_scalef32_pk_f32_fp4 v[224:225], v193, 1.0
	v_cvt_scalef32_pk_f32_fp4 v[226:227], v197, 1.0
	v_pk_fma_f32 v[232:233], v[14:15], v[228:229], v[232:233]
	v_pk_fma_f32 v[234:235], v[14:15], v[230:231], v[234:235]
	v_cvt_scalef32_pk_f32_fp4 v[228:229], v193, 1.0 op_sel:[1,0,0]
	v_cvt_scalef32_pk_f32_fp4 v[230:231], v197, 1.0 op_sel:[1,0,0]
	v_pk_fma_f32 v[232:233], v[4:5], v[224:225], v[232:233]
	v_pk_fma_f32 v[234:235], v[4:5], v[226:227], v[234:235]
	v_cvt_scalef32_pk_f32_fp4 v[224:225], v193, 1.0 op_sel:[0,1,0]
	v_cvt_scalef32_pk_f32_fp4 v[226:227], v197, 1.0 op_sel:[0,1,0]
	v_pk_fma_f32 v[232:233], v[6:7], v[228:229], v[232:233]
	v_pk_fma_f32 v[234:235], v[6:7], v[230:231], v[234:235]
	v_cvt_scalef32_pk_f32_fp4 v[228:229], v193, 1.0 op_sel:[1,1,0]
	v_cvt_scalef32_pk_f32_fp4 v[230:231], v197, 1.0 op_sel:[1,1,0]
	v_pk_fma_f32 v[232:233], v[0:1], v[224:225], v[232:233]
	v_pk_fma_f32 v[234:235], v[0:1], v[226:227], v[234:235]
	v_cvt_scalef32_pk_f32_fp4 v[224:225], v194, 1.0
	v_cvt_scalef32_pk_f32_fp4 v[226:227], v198, 1.0
	v_pk_fma_f32 v[232:233], v[2:3], v[228:229], v[232:233]
	v_pk_fma_f32 v[234:235], v[2:3], v[230:231], v[234:235]
	v_cvt_scalef32_pk_f32_fp4 v[228:229], v194, 1.0 op_sel:[1,0,0]
	v_cvt_scalef32_pk_f32_fp4 v[230:231], v198, 1.0 op_sel:[1,0,0]
	v_pk_fma_f32 v[232:233], v[28:29], v[224:225], v[232:233]
	v_pk_fma_f32 v[234:235], v[28:29], v[226:227], v[234:235]
	v_cvt_scalef32_pk_f32_fp4 v[224:225], v194, 1.0 op_sel:[0,1,0]
	v_cvt_scalef32_pk_f32_fp4 v[226:227], v198, 1.0 op_sel:[0,1,0]
	v_pk_fma_f32 v[232:233], v[30:31], v[228:229], v[232:233]
	v_pk_fma_f32 v[234:235], v[30:31], v[230:231], v[234:235]
	v_cvt_scalef32_pk_f32_fp4 v[228:229], v194, 1.0 op_sel:[1,1,0]
	v_cvt_scalef32_pk_f32_fp4 v[230:231], v198, 1.0 op_sel:[1,1,0]
	v_pk_fma_f32 v[232:233], v[16:17], v[224:225], v[232:233]
	v_pk_fma_f32 v[234:235], v[16:17], v[226:227], v[234:235]
	v_cvt_scalef32_pk_f32_fp4 v[224:225], v195, 1.0
	v_cvt_scalef32_pk_f32_fp4 v[226:227], v199, 1.0
	v_pk_fma_f32 v[232:233], v[18:19], v[228:229], v[232:233]
	v_pk_fma_f32 v[234:235], v[18:19], v[230:231], v[234:235]
	v_cvt_scalef32_pk_f32_fp4 v[228:229], v195, 1.0 op_sel:[1,0,0]
	v_cvt_scalef32_pk_f32_fp4 v[230:231], v199, 1.0 op_sel:[1,0,0]
	v_pk_fma_f32 v[232:233], v[8:9], v[224:225], v[232:233]
	v_pk_fma_f32 v[234:235], v[8:9], v[226:227], v[234:235]
	v_cvt_scalef32_pk_f32_fp4 v[224:225], v195, 1.0 op_sel:[0,1,0]
	v_cvt_scalef32_pk_f32_fp4 v[226:227], v199, 1.0 op_sel:[0,1,0]
	v_pk_fma_f32 v[232:233], v[10:11], v[228:229], v[232:233]
	v_pk_fma_f32 v[234:235], v[10:11], v[230:231], v[234:235]
	v_cvt_scalef32_pk_f32_fp4 v[228:229], v195, 1.0 op_sel:[1,1,0]
	v_cvt_scalef32_pk_f32_fp4 v[230:231], v199, 1.0 op_sel:[1,1,0]
	v_pk_fma_f32 v[232:233], v[20:21], v[224:225], v[232:233]
	v_pk_fma_f32 v[234:235], v[20:21], v[226:227], v[234:235]
	v_pk_fma_f32 v[232:233], v[22:23], v[228:229], v[232:233]
	v_pk_fma_f32 v[234:235], v[22:23], v[230:231], v[234:235]
	v_add_f32_e32 v32, v232, v233
	v_add_f32_e32 v33, v234, v235
	s_waitcnt vmcnt(4)
	v_cvt_scalef32_pk_f32_fp4 v[224:225], v200, 1.0
	v_cvt_scalef32_pk_f32_fp4 v[226:227], v204, 1.0
	v_cvt_scalef32_pk_f32_fp4 v[228:229], v200, 1.0 op_sel:[1,0,0]
	v_cvt_scalef32_pk_f32_fp4 v[230:231], v204, 1.0 op_sel:[1,0,0]
	v_pk_fma_f32 v[236:237], v[24:25], v[224:225], 0 op_sel_hi:[1,1,0]
	v_pk_fma_f32 v[238:239], v[24:25], v[226:227], 0 op_sel_hi:[1,1,0]
	v_cvt_scalef32_pk_f32_fp4 v[224:225], v200, 1.0 op_sel:[0,1,0]
	v_cvt_scalef32_pk_f32_fp4 v[226:227], v204, 1.0 op_sel:[0,1,0]
	v_pk_fma_f32 v[236:237], v[26:27], v[228:229], v[236:237]
	v_pk_fma_f32 v[238:239], v[26:27], v[230:231], v[238:239]
	v_cvt_scalef32_pk_f32_fp4 v[228:229], v200, 1.0 op_sel:[1,1,0]
	v_cvt_scalef32_pk_f32_fp4 v[230:231], v204, 1.0 op_sel:[1,1,0]
	v_pk_fma_f32 v[236:237], v[12:13], v[224:225], v[236:237]
	v_pk_fma_f32 v[238:239], v[12:13], v[226:227], v[238:239]
	v_cvt_scalef32_pk_f32_fp4 v[224:225], v201, 1.0
	v_cvt_scalef32_pk_f32_fp4 v[226:227], v205, 1.0
	v_pk_fma_f32 v[236:237], v[14:15], v[228:229], v[236:237]
	v_pk_fma_f32 v[238:239], v[14:15], v[230:231], v[238:239]
	v_cvt_scalef32_pk_f32_fp4 v[228:229], v201, 1.0 op_sel:[1,0,0]
	v_cvt_scalef32_pk_f32_fp4 v[230:231], v205, 1.0 op_sel:[1,0,0]
	v_pk_fma_f32 v[236:237], v[4:5], v[224:225], v[236:237]
	v_pk_fma_f32 v[238:239], v[4:5], v[226:227], v[238:239]
	v_cvt_scalef32_pk_f32_fp4 v[224:225], v201, 1.0 op_sel:[0,1,0]
	v_cvt_scalef32_pk_f32_fp4 v[226:227], v205, 1.0 op_sel:[0,1,0]
	v_pk_fma_f32 v[236:237], v[6:7], v[228:229], v[236:237]
	v_pk_fma_f32 v[238:239], v[6:7], v[230:231], v[238:239]
	v_cvt_scalef32_pk_f32_fp4 v[228:229], v201, 1.0 op_sel:[1,1,0]
	v_cvt_scalef32_pk_f32_fp4 v[230:231], v205, 1.0 op_sel:[1,1,0]
	v_pk_fma_f32 v[236:237], v[0:1], v[224:225], v[236:237]
	v_pk_fma_f32 v[238:239], v[0:1], v[226:227], v[238:239]
	v_cvt_scalef32_pk_f32_fp4 v[224:225], v202, 1.0
	v_cvt_scalef32_pk_f32_fp4 v[226:227], v206, 1.0
	v_pk_fma_f32 v[236:237], v[2:3], v[228:229], v[236:237]
	v_pk_fma_f32 v[238:239], v[2:3], v[230:231], v[238:239]
	v_cvt_scalef32_pk_f32_fp4 v[228:229], v202, 1.0 op_sel:[1,0,0]
	v_cvt_scalef32_pk_f32_fp4 v[230:231], v206, 1.0 op_sel:[1,0,0]
	v_pk_fma_f32 v[236:237], v[28:29], v[224:225], v[236:237]
	v_pk_fma_f32 v[238:239], v[28:29], v[226:227], v[238:239]
	v_cvt_scalef32_pk_f32_fp4 v[224:225], v202, 1.0 op_sel:[0,1,0]
	v_cvt_scalef32_pk_f32_fp4 v[226:227], v206, 1.0 op_sel:[0,1,0]
	v_pk_fma_f32 v[236:237], v[30:31], v[228:229], v[236:237]
	v_pk_fma_f32 v[238:239], v[30:31], v[230:231], v[238:239]
	v_cvt_scalef32_pk_f32_fp4 v[228:229], v202, 1.0 op_sel:[1,1,0]
	v_cvt_scalef32_pk_f32_fp4 v[230:231], v206, 1.0 op_sel:[1,1,0]
	v_pk_fma_f32 v[236:237], v[16:17], v[224:225], v[236:237]
	v_pk_fma_f32 v[238:239], v[16:17], v[226:227], v[238:239]
	v_cvt_scalef32_pk_f32_fp4 v[224:225], v203, 1.0
	v_cvt_scalef32_pk_f32_fp4 v[226:227], v207, 1.0
	v_pk_fma_f32 v[236:237], v[18:19], v[228:229], v[236:237]
	v_pk_fma_f32 v[238:239], v[18:19], v[230:231], v[238:239]
	v_cvt_scalef32_pk_f32_fp4 v[228:229], v203, 1.0 op_sel:[1,0,0]
	v_cvt_scalef32_pk_f32_fp4 v[230:231], v207, 1.0 op_sel:[1,0,0]
	v_pk_fma_f32 v[236:237], v[8:9], v[224:225], v[236:237]
	v_pk_fma_f32 v[238:239], v[8:9], v[226:227], v[238:239]
	v_cvt_scalef32_pk_f32_fp4 v[224:225], v203, 1.0 op_sel:[0,1,0]
	v_cvt_scalef32_pk_f32_fp4 v[226:227], v207, 1.0 op_sel:[0,1,0]
	v_pk_fma_f32 v[236:237], v[10:11], v[228:229], v[236:237]
	v_pk_fma_f32 v[238:239], v[10:11], v[230:231], v[238:239]
	v_cvt_scalef32_pk_f32_fp4 v[228:229], v203, 1.0 op_sel:[1,1,0]
	v_cvt_scalef32_pk_f32_fp4 v[230:231], v207, 1.0 op_sel:[1,1,0]
	v_pk_fma_f32 v[236:237], v[20:21], v[224:225], v[236:237]
	v_pk_fma_f32 v[238:239], v[20:21], v[226:227], v[238:239]
	v_pk_fma_f32 v[236:237], v[22:23], v[228:229], v[236:237]
	v_pk_fma_f32 v[238:239], v[22:23], v[230:231], v[238:239]
	v_add_f32_e32 v34, v236, v237
	v_add_f32_e32 v35, v238, v239
	s_nop 1
	v_permlane16_swap_b32_e32 v32, v34
	v_permlane16_swap_b32_e32 v33, v35
	v_add_f32_e32 v36, v32, v34
	v_add_f32_e32 v38, v33, v35
	s_waitcnt lgkmcnt(0)
	v_cndmask_b32_e64 v40, v38, v36, s[0:1]
	v_cndmask_b32_e64 v41, v36, v38, s[0:1]
	s_nop 1
	v_add_f32_dpp v40, v41, v40 row_ror:8 row_mask:0xf bank_mask:0xf
	s_nop 1
	v_add_f32_dpp v40, v40, v40 quad_perm:[1,0,3,2] row_mask:0xf bank_mask:0xf
	s_nop 1
	v_add_f32_dpp v40, v40, v40 quad_perm:[2,3,0,1] row_mask:0xf bank_mask:0xf
	s_nop 1
	v_add_f32_dpp v40, v40, v40 row_half_mirror row_mask:0xf bank_mask:0xf
	v_mul_f32_e32 v42, v40, v156
	v_fma_f32 v43, |v42|, s16, 1.0
	v_rcp_f32_e32 v43, v43
	v_cmp_gt_f32_e64 s[4:5], 0, v42
	v_mul_f32_e32 v45, v42, v42
	v_fmamk_f32 v44, v43, 0x3f07dc22, v142
	v_fmaak_f32 v44, v43, v44, 0x3f35f0e3
	v_fmaak_f32 v44, v43, v44, 0xbe11a98e
	v_fmaak_f32 v44, v43, v44, 0x3e027906
	v_mul_f32_e32 v45, 0xbf38aa3b, v45
	v_exp_f32_e32 v45, v45
	v_mul_f32_e32 v43, v43, v44
	v_mul_f32_e32 v43, v45, v43
	v_mul_f32_e32 v44, v42, v43
	v_fma_f32 v42, -v42, v43, v42
	v_cndmask_b32_e64 v42, v42, v44, s[4:5]
	v_mul_f32_e32 v158, v42, v157
	ds_bpermute_b32 v118, v138, v158
	ds_bpermute_b32 v120, v139, v158
	ds_bpermute_b32 v122, v140, v158
	ds_bpermute_b32 v124, v141, v158
	s_waitcnt vmcnt(3)
	v_cvt_scalef32_pk_f32_fp4 v[224:225], v208, 1.0
	v_cvt_scalef32_pk_f32_fp4 v[226:227], v208, 1.0 op_sel:[1,0,0]
	s_waitcnt lgkmcnt(0)
	v_cvt_scalef32_pk_f32_fp4 v[228:229], v208, 1.0 op_sel:[0,1,0]
	v_pk_fma_f32 v[112:113], v[224:225], v[118:119], v[112:113] op_sel_hi:[1,0,1]
	v_cvt_scalef32_pk_f32_fp4 v[230:231], v208, 1.0 op_sel:[1,1,0]
	v_pk_fma_f32 v[108:109], v[226:227], v[118:119], v[108:109] op_sel_hi:[1,0,1]
	v_cvt_scalef32_pk_f32_fp4 v[224:225], v209, 1.0
	v_pk_fma_f32 v[104:105], v[228:229], v[118:119], v[104:105] op_sel_hi:[1,0,1]
	v_cvt_scalef32_pk_f32_fp4 v[226:227], v209, 1.0 op_sel:[1,0,0]
	v_pk_fma_f32 v[98:99], v[230:231], v[118:119], v[98:99] op_sel_hi:[1,0,1]
	v_cvt_scalef32_pk_f32_fp4 v[228:229], v209, 1.0 op_sel:[0,1,0]
	v_pk_fma_f32 v[54:55], v[224:225], v[118:119], v[54:55] op_sel_hi:[1,0,1]
	v_cvt_scalef32_pk_f32_fp4 v[230:231], v209, 1.0 op_sel:[1,1,0]
	v_pk_fma_f32 v[58:59], v[226:227], v[118:119], v[58:59] op_sel_hi:[1,0,1]
	v_cvt_scalef32_pk_f32_fp4 v[224:225], v210, 1.0
	v_pk_fma_f32 v[52:53], v[228:229], v[118:119], v[52:53] op_sel_hi:[1,0,1]
	v_cvt_scalef32_pk_f32_fp4 v[226:227], v210, 1.0 op_sel:[1,0,0]
	v_pk_fma_f32 v[48:49], v[230:231], v[118:119], v[48:49] op_sel_hi:[1,0,1]
	v_cvt_scalef32_pk_f32_fp4 v[228:229], v210, 1.0 op_sel:[0,1,0]
	v_pk_fma_f32 v[106:107], v[224:225], v[118:119], v[106:107] op_sel_hi:[1,0,1]
	v_cvt_scalef32_pk_f32_fp4 v[230:231], v210, 1.0 op_sel:[1,1,0]
	v_pk_fma_f32 v[102:103], v[226:227], v[118:119], v[102:103] op_sel_hi:[1,0,1]
	v_cvt_scalef32_pk_f32_fp4 v[224:225], v211, 1.0
	v_pk_fma_f32 v[96:97], v[228:229], v[118:119], v[96:97] op_sel_hi:[1,0,1]
	v_cvt_scalef32_pk_f32_fp4 v[226:227], v211, 1.0 op_sel:[1,0,0]
	v_pk_fma_f32 v[56:57], v[230:231], v[118:119], v[56:57] op_sel_hi:[1,0,1]
	v_cvt_scalef32_pk_f32_fp4 v[228:229], v211, 1.0 op_sel:[0,1,0]
	v_pk_fma_f32 v[50:51], v[224:225], v[118:119], v[50:51] op_sel_hi:[1,0,1]
	v_cvt_scalef32_pk_f32_fp4 v[230:231], v211, 1.0 op_sel:[1,1,0]
	v_pk_fma_f32 v[114:115], v[226:227], v[118:119], v[114:115] op_sel_hi:[1,0,1]
	v_pk_fma_f32 v[110:111], v[228:229], v[118:119], v[110:111] op_sel_hi:[1,0,1]
	v_pk_fma_f32 v[100:101], v[230:231], v[118:119], v[100:101] op_sel_hi:[1,0,1]
	s_waitcnt vmcnt(2)
	v_cvt_scalef32_pk_f32_fp4 v[224:225], v212, 1.0
	v_cvt_scalef32_pk_f32_fp4 v[226:227], v212, 1.0 op_sel:[1,0,0]
	v_cvt_scalef32_pk_f32_fp4 v[228:229], v212, 1.0 op_sel:[0,1,0]
	v_pk_fma_f32 v[112:113], v[224:225], v[120:121], v[112:113] op_sel_hi:[1,0,1]
	v_cvt_scalef32_pk_f32_fp4 v[230:231], v212, 1.0 op_sel:[1,1,0]
	v_pk_fma_f32 v[108:109], v[226:227], v[120:121], v[108:109] op_sel_hi:[1,0,1]
	v_cvt_scalef32_pk_f32_fp4 v[224:225], v213, 1.0
	v_pk_fma_f32 v[104:105], v[228:229], v[120:121], v[104:105] op_sel_hi:[1,0,1]
	v_cvt_scalef32_pk_f32_fp4 v[226:227], v213, 1.0 op_sel:[1,0,0]
	v_pk_fma_f32 v[98:99], v[230:231], v[120:121], v[98:99] op_sel_hi:[1,0,1]
	v_cvt_scalef32_pk_f32_fp4 v[228:229], v213, 1.0 op_sel:[0,1,0]
	v_pk_fma_f32 v[54:55], v[224:225], v[120:121], v[54:55] op_sel_hi:[1,0,1]
	v_cvt_scalef32_pk_f32_fp4 v[230:231], v213, 1.0 op_sel:[1,1,0]
	v_pk_fma_f32 v[58:59], v[226:227], v[120:121], v[58:59] op_sel_hi:[1,0,1]
	v_cvt_scalef32_pk_f32_fp4 v[224:225], v214, 1.0
	v_pk_fma_f32 v[52:53], v[228:229], v[120:121], v[52:53] op_sel_hi:[1,0,1]
	v_cvt_scalef32_pk_f32_fp4 v[226:227], v214, 1.0 op_sel:[1,0,0]
	v_pk_fma_f32 v[48:49], v[230:231], v[120:121], v[48:49] op_sel_hi:[1,0,1]
	v_cvt_scalef32_pk_f32_fp4 v[228:229], v214, 1.0 op_sel:[0,1,0]
	v_pk_fma_f32 v[106:107], v[224:225], v[120:121], v[106:107] op_sel_hi:[1,0,1]
	v_cvt_scalef32_pk_f32_fp4 v[230:231], v214, 1.0 op_sel:[1,1,0]
	v_pk_fma_f32 v[102:103], v[226:227], v[120:121], v[102:103] op_sel_hi:[1,0,1]
	v_cvt_scalef32_pk_f32_fp4 v[224:225], v215, 1.0
	v_pk_fma_f32 v[96:97], v[228:229], v[120:121], v[96:97] op_sel_hi:[1,0,1]
	v_cvt_scalef32_pk_f32_fp4 v[226:227], v215, 1.0 op_sel:[1,0,0]
	v_pk_fma_f32 v[56:57], v[230:231], v[120:121], v[56:57] op_sel_hi:[1,0,1]
	v_cvt_scalef32_pk_f32_fp4 v[228:229], v215, 1.0 op_sel:[0,1,0]
	v_pk_fma_f32 v[50:51], v[224:225], v[120:121], v[50:51] op_sel_hi:[1,0,1]
	v_cvt_scalef32_pk_f32_fp4 v[230:231], v215, 1.0 op_sel:[1,1,0]
	v_pk_fma_f32 v[114:115], v[226:227], v[120:121], v[114:115] op_sel_hi:[1,0,1]
	v_pk_fma_f32 v[110:111], v[228:229], v[120:121], v[110:111] op_sel_hi:[1,0,1]
	v_pk_fma_f32 v[100:101], v[230:231], v[120:121], v[100:101] op_sel_hi:[1,0,1]
	s_waitcnt vmcnt(1)
	v_cvt_scalef32_pk_f32_fp4 v[224:225], v216, 1.0
	v_cvt_scalef32_pk_f32_fp4 v[226:227], v216, 1.0 op_sel:[1,0,0]
	v_cvt_scalef32_pk_f32_fp4 v[228:229], v216, 1.0 op_sel:[0,1,0]
	v_pk_fma_f32 v[112:113], v[224:225], v[122:123], v[112:113] op_sel_hi:[1,0,1]
	v_cvt_scalef32_pk_f32_fp4 v[230:231], v216, 1.0 op_sel:[1,1,0]
	v_pk_fma_f32 v[108:109], v[226:227], v[122:123], v[108:109] op_sel_hi:[1,0,1]
	v_cvt_scalef32_pk_f32_fp4 v[224:225], v217, 1.0
	v_pk_fma_f32 v[104:105], v[228:229], v[122:123], v[104:105] op_sel_hi:[1,0,1]
	v_cvt_scalef32_pk_f32_fp4 v[226:227], v217, 1.0 op_sel:[1,0,0]
	v_pk_fma_f32 v[98:99], v[230:231], v[122:123], v[98:99] op_sel_hi:[1,0,1]
	v_cvt_scalef32_pk_f32_fp4 v[228:229], v217, 1.0 op_sel:[0,1,0]
	v_pk_fma_f32 v[54:55], v[224:225], v[122:123], v[54:55] op_sel_hi:[1,0,1]
	v_cvt_scalef32_pk_f32_fp4 v[230:231], v217, 1.0 op_sel:[1,1,0]
	v_pk_fma_f32 v[58:59], v[226:227], v[122:123], v[58:59] op_sel_hi:[1,0,1]
	v_cvt_scalef32_pk_f32_fp4 v[224:225], v218, 1.0
	v_pk_fma_f32 v[52:53], v[228:229], v[122:123], v[52:53] op_sel_hi:[1,0,1]
	v_cvt_scalef32_pk_f32_fp4 v[226:227], v218, 1.0 op_sel:[1,0,0]
	v_pk_fma_f32 v[48:49], v[230:231], v[122:123], v[48:49] op_sel_hi:[1,0,1]
	v_cvt_scalef32_pk_f32_fp4 v[228:229], v218, 1.0 op_sel:[0,1,0]
	v_pk_fma_f32 v[106:107], v[224:225], v[122:123], v[106:107] op_sel_hi:[1,0,1]
	v_cvt_scalef32_pk_f32_fp4 v[230:231], v218, 1.0 op_sel:[1,1,0]
	v_pk_fma_f32 v[102:103], v[226:227], v[122:123], v[102:103] op_sel_hi:[1,0,1]
	v_cvt_scalef32_pk_f32_fp4 v[224:225], v219, 1.0
	v_pk_fma_f32 v[96:97], v[228:229], v[122:123], v[96:97] op_sel_hi:[1,0,1]
	v_cvt_scalef32_pk_f32_fp4 v[226:227], v219, 1.0 op_sel:[1,0,0]
	v_pk_fma_f32 v[56:57], v[230:231], v[122:123], v[56:57] op_sel_hi:[1,0,1]
	v_cvt_scalef32_pk_f32_fp4 v[228:229], v219, 1.0 op_sel:[0,1,0]
	v_pk_fma_f32 v[50:51], v[224:225], v[122:123], v[50:51] op_sel_hi:[1,0,1]
	v_cvt_scalef32_pk_f32_fp4 v[230:231], v219, 1.0 op_sel:[1,1,0]
	v_pk_fma_f32 v[114:115], v[226:227], v[122:123], v[114:115] op_sel_hi:[1,0,1]
	v_pk_fma_f32 v[110:111], v[228:229], v[122:123], v[110:111] op_sel_hi:[1,0,1]
	v_pk_fma_f32 v[100:101], v[230:231], v[122:123], v[100:101] op_sel_hi:[1,0,1]
	s_waitcnt vmcnt(0)
	v_cvt_scalef32_pk_f32_fp4 v[224:225], v220, 1.0
	v_cvt_scalef32_pk_f32_fp4 v[226:227], v220, 1.0 op_sel:[1,0,0]
	v_cvt_scalef32_pk_f32_fp4 v[228:229], v220, 1.0 op_sel:[0,1,0]
	v_pk_fma_f32 v[112:113], v[224:225], v[124:125], v[112:113] op_sel_hi:[1,0,1]
	v_cvt_scalef32_pk_f32_fp4 v[230:231], v220, 1.0 op_sel:[1,1,0]
	v_pk_fma_f32 v[108:109], v[226:227], v[124:125], v[108:109] op_sel_hi:[1,0,1]
	v_cvt_scalef32_pk_f32_fp4 v[224:225], v221, 1.0
	v_pk_fma_f32 v[104:105], v[228:229], v[124:125], v[104:105] op_sel_hi:[1,0,1]
	v_cvt_scalef32_pk_f32_fp4 v[226:227], v221, 1.0 op_sel:[1,0,0]
	v_pk_fma_f32 v[98:99], v[230:231], v[124:125], v[98:99] op_sel_hi:[1,0,1]
	v_cvt_scalef32_pk_f32_fp4 v[228:229], v221, 1.0 op_sel:[0,1,0]
	v_pk_fma_f32 v[54:55], v[224:225], v[124:125], v[54:55] op_sel_hi:[1,0,1]
	v_cvt_scalef32_pk_f32_fp4 v[230:231], v221, 1.0 op_sel:[1,1,0]
	v_pk_fma_f32 v[58:59], v[226:227], v[124:125], v[58:59] op_sel_hi:[1,0,1]
	v_cvt_scalef32_pk_f32_fp4 v[224:225], v222, 1.0
	v_pk_fma_f32 v[52:53], v[228:229], v[124:125], v[52:53] op_sel_hi:[1,0,1]
	v_cvt_scalef32_pk_f32_fp4 v[226:227], v222, 1.0 op_sel:[1,0,0]
	v_pk_fma_f32 v[48:49], v[230:231], v[124:125], v[48:49] op_sel_hi:[1,0,1]
	v_cvt_scalef32_pk_f32_fp4 v[228:229], v222, 1.0 op_sel:[0,1,0]
	v_pk_fma_f32 v[106:107], v[224:225], v[124:125], v[106:107] op_sel_hi:[1,0,1]
	v_cvt_scalef32_pk_f32_fp4 v[230:231], v222, 1.0 op_sel:[1,1,0]
	v_pk_fma_f32 v[102:103], v[226:227], v[124:125], v[102:103] op_sel_hi:[1,0,1]
	v_cvt_scalef32_pk_f32_fp4 v[224:225], v223, 1.0
	v_pk_fma_f32 v[96:97], v[228:229], v[124:125], v[96:97] op_sel_hi:[1,0,1]
	v_cvt_scalef32_pk_f32_fp4 v[226:227], v223, 1.0 op_sel:[1,0,0]
	v_pk_fma_f32 v[56:57], v[230:231], v[124:125], v[56:57] op_sel_hi:[1,0,1]
	v_cvt_scalef32_pk_f32_fp4 v[228:229], v223, 1.0 op_sel:[0,1,0]
	v_pk_fma_f32 v[50:51], v[224:225], v[124:125], v[50:51] op_sel_hi:[1,0,1]
	v_cvt_scalef32_pk_f32_fp4 v[230:231], v223, 1.0 op_sel:[1,1,0]
	v_pk_fma_f32 v[114:115], v[226:227], v[124:125], v[114:115] op_sel_hi:[1,0,1]
	v_pk_fma_f32 v[110:111], v[228:229], v[124:125], v[110:111] op_sel_hi:[1,0,1]
	v_pk_fma_f32 v[100:101], v[230:231], v[124:125], v[100:101] op_sel_hi:[1,0,1]
	ds_bpermute_b32 v32, v135, v112
	ds_bpermute_b32 v33, v135, v113
	ds_bpermute_b32 v126, v135, v110
	ds_bpermute_b32 v127, v135, v111
	ds_bpermute_b32 v116, v135, v106
	ds_bpermute_b32 v117, v135, v107
	ds_bpermute_b32 v34, v135, v108
	ds_bpermute_b32 v35, v135, v109
	ds_bpermute_b32 v118, v135, v102
	ds_bpermute_b32 v119, v135, v103
	s_waitcnt lgkmcnt(8)
	v_pk_add_f32 v[32:33], v[112:113], v[32:33]
	s_waitcnt lgkmcnt(6)
	v_pk_add_f32 v[110:111], v[110:111], v[126:127]
	v_pk_fma_f32 v[24:25], v[24:25], s[12:13], v[32:33] op_sel_hi:[1,0,1]
	v_pk_fma_f32 v[20:21], v[20:21], s[12:13], v[110:111] op_sel_hi:[1,0,1]
	ds_bpermute_b32 v110, v135, v100
	ds_bpermute_b32 v111, v135, v101
	v_add_f32_e32 v32, 0, v24
	ds_bpermute_b32 v36, v135, v104
	ds_bpermute_b32 v37, v135, v105
	v_add_f32_e32 v64, v32, v25
	s_waitcnt lgkmcnt(8)
	v_pk_add_f32 v[32:33], v[106:107], v[116:117]
	ds_bpermute_b32 v120, v135, v96
	ds_bpermute_b32 v121, v135, v97
	v_pk_fma_f32 v[28:29], v[28:29], s[12:13], v[32:33] op_sel_hi:[1,0,1]
	s_waitcnt lgkmcnt(8)
	v_pk_add_f32 v[32:33], v[108:109], v[34:35]
	ds_bpermute_b32 v38, v135, v98
	v_pk_fma_f32 v[26:27], v[26:27], s[12:13], v[32:33] op_sel_hi:[1,0,1]
	s_waitcnt lgkmcnt(7)
	v_pk_add_f32 v[32:33], v[102:103], v[118:119]
	ds_bpermute_b32 v39, v135, v99
	v_pk_fma_f32 v[30:31], v[30:31], s[12:13], v[32:33] op_sel_hi:[1,0,1]
	v_add_f32_e32 v32, v64, v26
	ds_bpermute_b32 v122, v135, v56
	ds_bpermute_b32 v123, v135, v57
	v_add_f32_e32 v34, v32, v27
	s_waitcnt lgkmcnt(8)
	v_pk_add_f32 v[32:33], v[100:101], v[110:111]
	ds_bpermute_b32 v40, v135, v54
	v_pk_fma_f32 v[22:23], v[22:23], s[12:13], v[32:33] op_sel_hi:[1,0,1]
	s_waitcnt lgkmcnt(7)
	v_pk_add_f32 v[32:33], v[104:105], v[36:37]
	ds_bpermute_b32 v41, v135, v55
	v_pk_fma_f32 v[12:13], v[12:13], s[12:13], v[32:33] op_sel_hi:[1,0,1]
	s_waitcnt lgkmcnt(6)
	v_pk_add_f32 v[32:33], v[96:97], v[120:121]
	ds_bpermute_b32 v128, v135, v50
	ds_bpermute_b32 v129, v135, v51
	v_pk_fma_f32 v[16:17], v[16:17], s[12:13], v[32:33] op_sel_hi:[1,0,1]
	v_add_f32_e32 v32, v34, v12
	v_add_f32_e32 v34, v32, v13
	s_waitcnt lgkmcnt(6)
	v_pk_add_f32 v[32:33], v[98:99], v[38:39]
	ds_bpermute_b32 v42, v135, v58
	ds_bpermute_b32 v43, v135, v59
	v_pk_fma_f32 v[14:15], v[14:15], s[12:13], v[32:33] op_sel_hi:[1,0,1]
	s_waitcnt lgkmcnt(6)
	v_pk_add_f32 v[32:33], v[56:57], v[122:123]
	ds_bpermute_b32 v44, v135, v52
	v_pk_fma_f32 v[18:19], v[18:19], s[12:13], v[32:33] op_sel_hi:[1,0,1]
	v_add_f32_e32 v32, v34, v14
	v_add_f32_e32 v34, v32, v15
	s_waitcnt lgkmcnt(5)
	v_pk_add_f32 v[32:33], v[54:55], v[40:41]
	ds_bpermute_b32 v45, v135, v53
	v_pk_fma_f32 v[32:33], v[4:5], s[12:13], v[32:33] op_sel_hi:[1,0,1]
	s_waitcnt lgkmcnt(4)
	v_pk_add_f32 v[4:5], v[50:51], v[128:129]
	ds_bpermute_b32 v46, v135, v48
	v_pk_fma_f32 v[8:9], v[8:9], s[12:13], v[4:5] op_sel_hi:[1,0,1]
	v_add_f32_e32 v4, v34, v32
	v_add_f32_e32 v36, v4, v33
	s_waitcnt lgkmcnt(3)
	v_pk_add_f32 v[4:5], v[58:59], v[42:43]
	ds_bpermute_b32 v47, v135, v49
	v_pk_fma_f32 v[34:35], v[6:7], s[12:13], v[4:5] op_sel_hi:[1,0,1]
	ds_bpermute_b32 v124, v135, v114
	v_add_f32_e32 v4, v36, v34
	v_add_f32_e32 v6, v4, v35
	s_waitcnt lgkmcnt(3)
	v_pk_add_f32 v[4:5], v[52:53], v[44:45]
	ds_bpermute_b32 v125, v135, v115
	v_pk_fma_f32 v[36:37], v[0:1], s[12:13], v[4:5] op_sel_hi:[1,0,1]
	v_mov_b32_e32 v92, v144
	v_add_f32_e32 v0, v6, v36
	v_add_f32_e32 v4, v0, v37
	s_waitcnt lgkmcnt(2)
	v_pk_add_f32 v[0:1], v[48:49], v[46:47]
	s_waitcnt lgkmcnt(0)
	v_pk_add_f32 v[114:115], v[114:115], v[124:125]
	v_pk_fma_f32 v[38:39], v[2:3], s[12:13], v[0:1] op_sel_hi:[1,0,1]
	v_pk_fma_f32 v[10:11], v[10:11], s[12:13], v[114:115] op_sel_hi:[1,0,1]
	v_add_f32_e32 v0, v4, v38
	v_add_f32_e32 v0, v0, v39
	v_add_f32_e32 v0, v0, v28
	v_add_f32_e32 v0, v0, v29
	v_add_f32_e32 v0, v0, v30
	v_add_f32_e32 v0, v0, v31
	v_add_f32_e32 v0, v0, v16
	v_add_f32_e32 v0, v0, v17
	v_add_f32_e32 v0, v0, v18
	v_add_f32_e32 v0, v0, v19
	v_add_f32_e32 v0, v0, v8
	v_add_f32_e32 v0, v0, v9
	v_add_f32_e32 v0, v0, v10
	v_add_f32_e32 v0, v0, v11
	v_add_f32_e32 v0, v0, v20
	v_add_f32_e32 v0, v0, v21
	v_add_f32_e32 v0, v0, v22
	v_add_f32_e32 v0, v0, v23
	ds_bpermute_b32 v1, v61, v0
	v_mov_b32_e32 v94, v145
	s_waitcnt lgkmcnt(0)
	v_add_f32_e32 v0, v0, v1
	ds_bpermute_b32 v1, v63, v0
	s_waitcnt lgkmcnt(0)
	v_add_f32_e32 v0, v0, v1
	ds_bpermute_b32 v1, v132, v0
	s_waitcnt lgkmcnt(0)
	v_add_f32_e32 v0, v0, v1
	ds_bpermute_b32 v1, v133, v0
	s_waitcnt lgkmcnt(0)
	v_add_f32_e32 v40, v0, v1
	ds_bpermute_b32 v41, v134, v40
	global_load_dwordx4 v[0:3], v[70:71], off
	global_load_dwordx4 v[4:7], v[72:73], off
	global_load_dwordx4 v[160:163], v[74:75], off
	global_load_dwordx4 v[164:167], v[76:77], off
	global_load_dwordx4 v[168:171], v[78:79], off
	global_load_dwordx4 v[172:175], v[80:81], off
	global_load_dwordx4 v[176:179], v[82:83], off
	global_load_dwordx4 v[180:183], v[84:85], off
	s_waitcnt lgkmcnt(0)
	v_add_f32_e32 v40, v40, v41
	v_mul_f32_e32 v40, 0x3a800000, v40
	v_pk_add_f32 v[24:25], v[24:25], v[40:41] op_sel_hi:[1,0] neg_lo:[0,1] neg_hi:[0,1]
	v_pk_add_f32 v[26:27], v[26:27], v[40:41] op_sel_hi:[1,0] neg_lo:[0,1] neg_hi:[0,1]
	v_pk_mul_f32 v[42:43], v[24:25], v[24:25]
	v_pk_mul_f32 v[44:45], v[26:27], v[26:27]
	v_add_f32_e32 v42, v42, v43
	v_pk_add_f32 v[12:13], v[12:13], v[40:41] op_sel_hi:[1,0] neg_lo:[0,1] neg_hi:[0,1]
	v_add_f32_e32 v42, v44, v42
	v_pk_mul_f32 v[46:47], v[12:13], v[12:13]
	v_add_f32_e32 v42, v45, v42
	v_pk_add_f32 v[14:15], v[14:15], v[40:41] op_sel_hi:[1,0] neg_lo:[0,1] neg_hi:[0,1]
	v_add_f32_e32 v42, v46, v42
	v_pk_mul_f32 v[48:49], v[14:15], v[14:15]
	v_add_f32_e32 v42, v47, v42
	v_pk_add_f32 v[32:33], v[32:33], v[40:41] op_sel_hi:[1,0] neg_lo:[0,1] neg_hi:[0,1]
	v_add_f32_e32 v42, v48, v42
	v_pk_mul_f32 v[50:51], v[32:33], v[32:33]
	v_add_f32_e32 v42, v49, v42
	v_pk_add_f32 v[34:35], v[34:35], v[40:41] op_sel_hi:[1,0] neg_lo:[0,1] neg_hi:[0,1]
	v_add_f32_e32 v42, v50, v42
	v_pk_mul_f32 v[52:53], v[34:35], v[34:35]
	v_add_f32_e32 v42, v51, v42
	v_pk_add_f32 v[36:37], v[36:37], v[40:41] op_sel_hi:[1,0] neg_lo:[0,1] neg_hi:[0,1]
	v_add_f32_e32 v42, v52, v42
	v_pk_mul_f32 v[54:55], v[36:37], v[36:37]
	v_add_f32_e32 v42, v53, v42
	v_pk_add_f32 v[38:39], v[38:39], v[40:41] op_sel_hi:[1,0] neg_lo:[0,1] neg_hi:[0,1]
	v_add_f32_e32 v42, v54, v42
	v_pk_mul_f32 v[56:57], v[38:39], v[38:39]
	v_add_f32_e32 v42, v55, v42
	v_pk_add_f32 v[28:29], v[28:29], v[40:41] op_sel_hi:[1,0] neg_lo:[0,1] neg_hi:[0,1]
	v_add_f32_e32 v42, v56, v42
	v_pk_mul_f32 v[58:59], v[28:29], v[28:29]
	v_add_f32_e32 v42, v57, v42
	v_pk_add_f32 v[30:31], v[30:31], v[40:41] op_sel_hi:[1,0] neg_lo:[0,1] neg_hi:[0,1]
	v_add_f32_e32 v42, v58, v42
	v_pk_mul_f32 v[96:97], v[30:31], v[30:31]
	v_add_f32_e32 v42, v59, v42
	v_pk_add_f32 v[16:17], v[16:17], v[40:41] op_sel_hi:[1,0] neg_lo:[0,1] neg_hi:[0,1]
	v_add_f32_e32 v42, v96, v42
	v_pk_mul_f32 v[98:99], v[16:17], v[16:17]
	v_add_f32_e32 v42, v97, v42
	v_pk_add_f32 v[18:19], v[18:19], v[40:41] op_sel_hi:[1,0] neg_lo:[0,1] neg_hi:[0,1]
	v_add_f32_e32 v42, v98, v42
	v_pk_mul_f32 v[100:101], v[18:19], v[18:19]
	v_add_f32_e32 v42, v99, v42
	v_pk_add_f32 v[8:9], v[8:9], v[40:41] op_sel_hi:[1,0] neg_lo:[0,1] neg_hi:[0,1]
	v_add_f32_e32 v42, v100, v42
	v_pk_mul_f32 v[102:103], v[8:9], v[8:9]
	v_add_f32_e32 v42, v101, v42
	v_pk_add_f32 v[10:11], v[10:11], v[40:41] op_sel_hi:[1,0] neg_lo:[0,1] neg_hi:[0,1]
	v_add_f32_e32 v42, v102, v42
	v_pk_mul_f32 v[104:105], v[10:11], v[10:11]
	v_add_f32_e32 v42, v103, v42
	v_pk_add_f32 v[20:21], v[20:21], v[40:41] op_sel_hi:[1,0] neg_lo:[0,1] neg_hi:[0,1]
	v_add_f32_e32 v42, v104, v42
	v_pk_mul_f32 v[106:107], v[20:21], v[20:21]
	v_add_f32_e32 v42, v105, v42
	v_pk_add_f32 v[22:23], v[22:23], v[40:41] op_sel_hi:[1,0] neg_lo:[0,1] neg_hi:[0,1]
	v_add_f32_e32 v42, v106, v42
	v_pk_mul_f32 v[40:41], v[22:23], v[22:23]
	v_add_f32_e32 v42, v107, v42
	v_add_f32_e32 v40, v40, v42
	v_add_f32_e32 v40, v41, v40
	ds_bpermute_b32 v41, v61, v40
	v_cndmask_b32_e64 v27, v31, v27, s[2:3]
	v_cndmask_b32_e64 v26, v30, v26, s[2:3]
	v_cndmask_b32_e64 v25, v29, v25, s[2:3]
	v_cndmask_b32_e64 v24, v28, v24, s[2:3]
	s_waitcnt lgkmcnt(0)
	v_add_f32_e32 v40, v40, v41
	ds_bpermute_b32 v41, v63, v40
	v_cndmask_b32_e64 v13, v17, v13, s[2:3]
	v_cndmask_b32_e64 v12, v16, v12, s[2:3]
	v_cndmask_b32_e64 v15, v19, v15, s[2:3]
	v_cndmask_b32_e64 v14, v18, v14, s[2:3]
	s_waitcnt lgkmcnt(0)
	v_add_f32_e32 v40, v40, v41
	ds_bpermute_b32 v41, v132, v40
	v_cndmask_b32_e64 v9, v9, v33, s[2:3]
	v_cndmask_b32_e64 v8, v8, v32, s[2:3]
	v_cndmask_b32_e64 v11, v11, v35, s[2:3]
	v_cndmask_b32_e64 v10, v10, v34, s[2:3]
	s_waitcnt lgkmcnt(0)
	v_add_f32_e32 v40, v40, v41
	ds_bpermute_b32 v41, v133, v40
	v_mov_b32_e32 v32, v95
	s_waitcnt lgkmcnt(0)
	v_add_f32_e32 v40, v40, v41
	ds_bpermute_b32 v41, v134, v40
	s_waitcnt lgkmcnt(0)
	v_add_f32_e32 v40, v40, v41
	v_fmamk_f32 v40, v40, 0x3a800000, v143
	v_mul_f32_e32 v41, 0x4b800000, v40
	v_cmp_gt_f32_e64 s[4:5], s17, v40
	s_nop 1
	v_cndmask_b32_e64 v40, v40, v41, s[4:5]
	v_rsq_f32_e32 v42, v40
	v_lshl_add_u64 v[40:41], v[88:89], 0, v[90:91]
	v_mul_f32_e32 v43, 0x45800000, v42
	v_cndmask_b32_e64 v42, v42, v43, s[4:5]
	v_pk_mul_f32 v[24:25], v[24:25], v[42:43] op_sel_hi:[1,0]
	v_pk_mul_f32 v[26:27], v[26:27], v[42:43] op_sel_hi:[1,0]
	s_waitcnt vmcnt(0)
	v_pk_fma_f32 v[0:1], v[0:1], v[24:25], v[4:5]
	v_pk_fma_f32 v[2:3], v[2:3], v[26:27], v[6:7]
	global_store_dwordx4 v[40:41], v[0:3], off
	v_pk_mul_f32 v[14:15], v[14:15], v[42:43] op_sel_hi:[1,0]
	v_pk_mul_f32 v[12:13], v[12:13], v[42:43] op_sel_hi:[1,0]
	v_pk_mul_f32 v[10:11], v[10:11], v[42:43] op_sel_hi:[1,0]
	v_pk_mul_f32 v[8:9], v[8:9], v[42:43] op_sel_hi:[1,0]
	v_pk_fma_f32 v[160:161], v[160:161], v[12:13], v[164:165]
	v_pk_fma_f32 v[162:163], v[162:163], v[14:15], v[166:167]
	global_store_dwordx4 v[40:41], v[160:163], off offset:16
	v_pk_fma_f32 v[168:169], v[168:169], v[8:9], v[172:173]
	v_pk_fma_f32 v[170:171], v[170:171], v[10:11], v[174:175]
	global_store_dwordx4 v[40:41], v[168:171], off offset:32
	v_cndmask_b32_e64 v9, v21, v37, s[2:3]
	v_cndmask_b32_e64 v8, v20, v36, s[2:3]
	v_cndmask_b32_e64 v11, v23, v39, s[2:3]
	v_cndmask_b32_e64 v10, v22, v38, s[2:3]
	v_pk_mul_f32 v[10:11], v[10:11], v[42:43] op_sel_hi:[1,0]
	v_pk_mul_f32 v[8:9], v[8:9], v[42:43] op_sel_hi:[1,0]
	v_pk_fma_f32 v[178:179], v[178:179], v[10:11], v[182:183]
	v_pk_fma_f32 v[176:177], v[176:177], v[8:9], v[180:181]
	global_store_dwordx4 v[40:41], v[176:179], off offset:48
	s_andn2_b64 exec, exec, s[10:11]
	s_cbranch_execnz .LBB0_698
